# trimmed DPP FFN-F2 epilogue plus conv FMA chains starting from the bias (61 packed adds fewer)
# baseline (speedup 1.0000x reference)
.LBB0_1060:
	s_lshl_b32 s0, s3, 8
	s_add_i32 s0, s0, s60
	s_cmpk_lt_i32 s0, 0x2000
	s_movk_i32 s20, 0xfff
	v_lshl_or_b32 v192, s2, 8, v223
	s_cselect_b32 s14, s20, 0x7ff
	s_or_b32 s2, s0, 63
	s_and_b32 s1, s14, s0
	s_and_b32 s15, s14, s2
	v_or_b32_e32 v226, s0, v221
	v_mov_b64_e32 v[208:209], s[10:11]
	s_movk_i32 s26, 0x2c00
	v_ashrrev_i32_e32 v193, 31, v192
	v_mad_i64_i32 v[152:153], s[2:3], v226, s26, v[208:209]
	s_cmp_eq_u32 s1, 0
	s_mul_i32 s1, s0, 0x2c00
	v_lshlrev_b64 v[204:205], 1, v[192:193]
	s_cselect_b64 s[62:63], -1, 0
	s_mul_hi_i32 s3, s0, 0x2c00
	s_add_u32 s2, s10, s1
	v_lshl_add_u64 v[194:195], v[152:153], 0, v[204:205]
	s_mov_b32 s21, 0x2c000
	s_addc_u32 s3, s11, s3
	v_add_co_u32_e32 v198, vcc, s21, v194
	s_and_b64 s[12:13], s[62:63], exec
	s_nop 0
	v_addc_co_u32_e32 v199, vcc, 0, v195, vcc
	s_mov_b32 s22, 0x58000
	s_cselect_b32 s12, 0, 0xffffd400
	s_cselect_b32 s13, 0, -1
	s_cmp_eq_u32 s15, s14
	v_add_co_u32_e32 v200, vcc, s22, v194
	s_cselect_b64 s[50:51], -1, 0
	v_lshlrev_b64 v[88:89], 2, v[192:193]
	v_addc_co_u32_e32 v201, vcc, 0, v195, vcc
	s_mov_b32 s23, 0x84000
	v_lshl_add_u64 v[202:203], s[2:3], 0, v[204:205]
	s_and_b64 s[2:3], s[50:51], exec
	v_lshl_add_u64 v[190:191], s[18:19], 0, v[88:89]
	v_lshl_add_u64 v[90:91], s[46:47], 0, v[88:89]
	v_lshl_add_u64 v[96:97], s[48:49], 0, v[88:89]
	v_add_co_u32_e32 v206, vcc, s23, v194
	s_cselect_b32 s72, 0, 0xb0000
	v_lshl_add_u64 v[188:189], s[30:31], 0, v[88:89]
	global_load_dwordx4 v[100:103], v[190:191], off offset:16
	global_load_dwordx4 v[120:123], v[190:191], off
	global_load_dwordx4 v[92:95], v[90:91], off offset:16
	global_load_dwordx4 v[112:115], v[90:91], off
	s_nop 0
	global_load_dwordx4 v[88:91], v[96:97], off offset:16
	global_load_dwordx4 v[108:111], v[96:97], off
	s_nop 0
	global_load_dwordx4 v[96:99], v[188:189], off offset:16
	global_load_dwordx4 v[116:119], v[188:189], off
	global_load_dwordx4 v[172:175], v[194:195], off
	v_addc_co_u32_e32 v207, vcc, 0, v195, vcc
	v_lshl_add_u64 v[196:197], v[202:203], 0, s[12:13]
	v_lshl_add_u64 v[202:203], v[202:203], 0, s[72:73]
	global_load_dwordx4 v[168:171], v[198:199], off
	global_load_dwordx4 v[164:167], v[200:201], off
	global_load_dwordx4 v[152:155], v[206:207], off
	global_load_dwordx4 v[232:235], v[202:203], off
	global_load_dwordx4 v[228:231], v[196:197], off
	v_or_b32_e32 v193, v211, v219
	v_lshlrev_b32_e32 v193, 2, v193
	v_or_b32_e32 v225, v219, v212
	v_lshlrev_b32_e32 v225, 2, v225
	s_add_i32 s12, s0, 0x80
	s_cmpk_lt_i32 s12, 0x2000
	s_cselect_b32 s13, s20, 0x7ff
	s_addk_i32 s0, 0xbf
	s_and_b32 s14, s13, s12
	s_and_b32 s15, s13, s0
	s_cmp_eq_u32 s14, 0
	s_waitcnt vmcnt(0)
	v_mov_b32_dpp v239, v172 row_ror:1 row_mask:0xf bank_mask:0xf
	v_mov_b32_dpp v240, v173 row_ror:1 row_mask:0xf bank_mask:0xf
	v_mov_b32_dpp v241, v174 row_ror:1 row_mask:0xf bank_mask:0xf
	v_mov_b32_dpp v242, v175 row_ror:1 row_mask:0xf bank_mask:0xf
	v_mov_b32_dpp v243, v168 row_ror:15 row_mask:0xf bank_mask:0xf
	v_mov_b32_dpp v244, v169 row_ror:15 row_mask:0xf bank_mask:0xf
	v_mov_b32_dpp v245, v170 row_ror:15 row_mask:0xf bank_mask:0xf
	v_cndmask_b32_e64 v227, v235, 0, s[50:51]
	v_cndmask_b32_e64 v236, v230, 0, s[62:63]
	v_cndmask_b32_e64 v237, v229, 0, s[62:63]
	v_cndmask_b32_e64 v229, v233, 0, s[50:51]
	v_cndmask_b32_e64 v230, v232, 0, s[50:51]
	v_mov_b32_dpp v232, v172 row_ror:15 row_mask:0xf bank_mask:0xf
	v_mov_b32_dpp v233, v173 row_ror:15 row_mask:0xf bank_mask:0xf
	v_cndmask_b32_e64 v238, v228, 0, s[62:63]
	v_cndmask_b32_e64 v228, v234, 0, s[50:51]
	v_mov_b32_dpp v234, v174 row_ror:15 row_mask:0xf bank_mask:0xf
	v_mov_b32_dpp v235, v175 row_ror:15 row_mask:0xf bank_mask:0xf
	v_mov_b32_dpp v246, v171 row_ror:15 row_mask:0xf bank_mask:0xf
	s_waitcnt lgkmcnt(0)
	v_cndmask_b32_e64 v238, v239, v238, s[4:5]
	v_cndmask_b32_e64 v247, v232, v243, s[6:7]
	v_cndmask_b32_e64 v249, v233, v244, s[6:7]
	v_lshlrev_b32_e32 v232, 16, v238
	v_and_b32_e32 v233, 0xffff0000, v238
	v_cndmask_b32_e64 v248, v240, v237, s[4:5]
	v_cndmask_b32_e64 v250, v241, v236, s[4:5]
	v_pk_fma_f32 v[232:233], v[120:121], v[232:233], v[116:117]
	v_lshlrev_b32_e32 v236, 16, v172
	v_and_b32_e32 v237, 0xffff0000, v172
	v_cndmask_b32_e64 v251, v234, v245, s[6:7]
	v_cndmask_b32_e64 v252, v235, v246, s[6:7]
	v_lshlrev_b32_e32 v234, 16, v247
	v_and_b32_e32 v235, 0xffff0000, v247
	v_pk_fma_f32 v[232:233], v[112:113], v[236:237], v[232:233]
	v_cndmask_b32_e64 v231, v231, 0, s[62:63]
	v_pk_fma_f32 v[232:233], v[108:109], v[234:235], v[232:233]
	v_cndmask_b32_e64 v231, v242, v231, s[4:5]
	v_mov_b32_dpp v236, v166 row_ror:15 row_mask:0xf bank_mask:0xf
	v_mul_f32_e32 v172, 0xbfb8aa3b, v232
	v_exp_f32_e32 v172, v172
	v_mov_b32_dpp v237, v167 row_ror:15 row_mask:0xf bank_mask:0xf
	v_add_f32_e32 v172, 1.0, v172
	v_rcp_f32_e32 v234, v172
	v_mul_f32_e32 v172, 0xbfb8aa3b, v233
	v_exp_f32_e32 v172, v172
	s_nop 0
	v_add_f32_e32 v172, 1.0, v172
	v_rcp_f32_e32 v235, v172
	v_lshlrev_b32_e32 v172, 16, v173
	v_and_b32_e32 v173, 0xffff0000, v173
	v_pk_mul_f32 v[232:233], v[232:233], v[234:235]
	s_nop 0
	v_pk_mul_f32 v[160:161], v[160:161], v[232:233]
	v_lshlrev_b32_e32 v232, 16, v248
	v_and_b32_e32 v233, 0xffff0000, v248
	v_pk_mul_f32 v[232:233], v[122:123], v[232:233]
	v_lshlrev_b32_e32 v234, 16, v249
	v_and_b32_e32 v235, 0xffff0000, v249
	v_pk_fma_f32 v[172:173], v[114:115], v[172:173], v[232:233]
	s_nop 0
	v_pk_fma_f32 v[172:173], v[110:111], v[234:235], v[172:173]
	v_lshlrev_b32_e32 v234, 16, v174
	v_pk_add_f32 v[172:173], v[118:119], v[172:173]
	v_and_b32_e32 v235, 0xffff0000, v174
	v_mul_f32_e32 v232, 0xbfb8aa3b, v172
	v_mul_f32_e32 v233, 0xbfb8aa3b, v173
	v_exp_f32_e32 v232, v232
	v_exp_f32_e32 v233, v233
	v_add_f32_e32 v232, 1.0, v232
	v_add_f32_e32 v233, 1.0, v233
	v_rcp_f32_e32 v232, v232
	v_rcp_f32_e32 v233, v233
	s_nop 0
	v_pk_mul_f32 v[172:173], v[172:173], v[232:233]
	s_nop 0
	v_pk_mul_f32 v[162:163], v[162:163], v[172:173]
	v_lshlrev_b32_e32 v172, 16, v250
	v_and_b32_e32 v173, 0xffff0000, v250
	v_pk_fma_f32 v[172:173], v[100:101], v[172:173], v[96:97]
	v_lshlrev_b32_e32 v232, 16, v251
	v_and_b32_e32 v233, 0xffff0000, v251
	v_pk_fma_f32 v[172:173], v[92:93], v[234:235], v[172:173]
	v_mov_b32_dpp v234, v164 row_ror:15 row_mask:0xf bank_mask:0xf
	v_pk_fma_f32 v[172:173], v[88:89], v[232:233], v[172:173]
	v_mov_b32_dpp v235, v165 row_ror:15 row_mask:0xf bank_mask:0xf
	s_nop 0
	v_mul_f32_e32 v174, 0xbfb8aa3b, v172
	v_exp_f32_e32 v174, v174
	s_nop 0
	v_add_f32_e32 v174, 1.0, v174
	v_rcp_f32_e32 v232, v174
	v_mul_f32_e32 v174, 0xbfb8aa3b, v173
	v_exp_f32_e32 v174, v174
	s_nop 0
	v_add_f32_e32 v174, 1.0, v174
	v_rcp_f32_e32 v233, v174
	v_lshlrev_b32_e32 v174, 16, v175
	v_and_b32_e32 v175, 0xffff0000, v175
	v_pk_mul_f32 v[172:173], v[172:173], v[232:233]
	s_nop 0
	v_pk_mul_f32 v[156:157], v[156:157], v[172:173]
	v_lshlrev_b32_e32 v172, 16, v231
	v_and_b32_e32 v173, 0xffff0000, v231
	v_pk_fma_f32 v[172:173], v[102:103], v[172:173], v[98:99]
	v_lshlrev_b32_e32 v232, 16, v252
	v_and_b32_e32 v233, 0xffff0000, v252
	v_pk_fma_f32 v[172:173], v[94:95], v[174:175], v[172:173]
	v_mov_b32_dpp v231, v170 row_ror:1 row_mask:0xf bank_mask:0xf
	v_pk_fma_f32 v[172:173], v[90:91], v[232:233], v[172:173]
	v_mov_b32_dpp v232, v171 row_ror:1 row_mask:0xf bank_mask:0xf
	v_or_b32_e32 v233, 16, v226
	v_mul_f32_e32 v174, 0xbfb8aa3b, v172
	v_mul_f32_e32 v175, 0xbfb8aa3b, v173
	v_exp_f32_e32 v174, v174
	v_exp_f32_e32 v175, v175
	v_cndmask_b32_e64 v242, v232, v242, s[4:5]
	v_add_f32_e32 v174, 1.0, v174
	v_add_f32_e32 v175, 1.0, v175
	v_rcp_f32_e32 v174, v174
	v_rcp_f32_e32 v175, v175
	s_nop 0
	v_pk_mul_f32 v[172:173], v[172:173], v[174:175]
	v_mov_b32_dpp v174, v168 row_ror:1 row_mask:0xf bank_mask:0xf
	v_pk_mul_f32 v[172:173], v[158:159], v[172:173]
	v_cvt_pk_bf16_f32 v158, v160, v161
	v_cvt_pk_bf16_f32 v161, v172, v173
	v_mov_b64_e32 v[172:173], s[16:17]
	v_cvt_pk_bf16_f32 v160, v156, v157
	v_mad_i64_i32 v[156:157], s[2:3], v226, s26, v[172:173]
	v_cvt_pk_bf16_f32 v159, v162, v163
	v_lshl_add_u64 v[156:157], v[156:157], 0, v[204:205]
	global_store_dwordx4 v[156:157], v[158:161], off
	v_lshlrev_b32_e32 v162, 16, v168
	v_and_b32_e32 v163, 0xffff0000, v168
	v_cndmask_b32_e64 v159, v174, v239, s[4:5]
	v_lshlrev_b32_e32 v158, 16, v159
	v_and_b32_e32 v159, 0xffff0000, v159
	v_cndmask_b32_e64 v161, v243, v234, s[6:7]
	v_pk_fma_f32 v[158:159], v[120:121], v[158:159], v[116:117]
	v_lshlrev_b32_e32 v160, 16, v161
	v_and_b32_e32 v161, 0xffff0000, v161
	v_pk_fma_f32 v[158:159], v[112:113], v[162:163], v[158:159]
	v_mov_b32_dpp v175, v169 row_ror:1 row_mask:0xf bank_mask:0xf
	v_pk_fma_f32 v[158:159], v[108:109], v[160:161], v[158:159]
	v_cndmask_b32_e64 v239, v244, v235, s[6:7]
	v_lshlrev_b32_e32 v162, 16, v169
	v_mul_f32_e32 v160, 0xbfb8aa3b, v158
	v_mul_f32_e32 v161, 0xbfb8aa3b, v159
	v_exp_f32_e32 v160, v160
	v_exp_f32_e32 v161, v161
	v_cndmask_b32_e64 v238, v175, v240, s[4:5]
	v_and_b32_e32 v163, 0xffff0000, v169
	v_add_f32_e32 v160, 1.0, v160
	v_add_f32_e32 v161, 1.0, v161
	v_rcp_f32_e32 v160, v160
	v_rcp_f32_e32 v161, v161
	v_cndmask_b32_e64 v240, v231, v241, s[4:5]
	v_cndmask_b32_e64 v241, v245, v236, s[6:7]
	v_cndmask_b32_e64 v243, v246, v237, s[6:7]
	v_pk_mul_f32 v[158:159], v[158:159], v[160:161]
	v_lshlrev_b32_e32 v160, 16, v239
	v_pk_mul_f32 v[148:149], v[148:149], v[158:159]
	v_lshlrev_b32_e32 v158, 16, v238
	v_and_b32_e32 v159, 0xffff0000, v238
	v_pk_fma_f32 v[158:159], v[122:123], v[158:159], v[118:119]
	v_and_b32_e32 v161, 0xffff0000, v239
	v_pk_fma_f32 v[158:159], v[114:115], v[162:163], v[158:159]
	v_lshlrev_b32_e32 v162, 16, v170
	v_pk_fma_f32 v[158:159], v[110:111], v[160:161], v[158:159]
	v_and_b32_e32 v163, 0xffff0000, v170
	v_cvt_pk_bf16_f32 v148, v148, v149
	v_mul_f32_e32 v160, 0xbfb8aa3b, v158
	v_mul_f32_e32 v161, 0xbfb8aa3b, v159
	v_exp_f32_e32 v160, v160
	v_exp_f32_e32 v161, v161
	v_mov_b32_dpp v168, v153 row_ror:15 row_mask:0xf bank_mask:0xf
	v_mov_b32_dpp v169, v154 row_ror:15 row_mask:0xf bank_mask:0xf
	v_add_f32_e32 v160, 1.0, v160
	v_add_f32_e32 v161, 1.0, v161
	v_rcp_f32_e32 v160, v160
	v_rcp_f32_e32 v161, v161
	v_mov_b32_dpp v170, v155 row_ror:15 row_mask:0xf bank_mask:0xf
	v_pk_mul_f32 v[158:159], v[158:159], v[160:161]
	s_nop 0
	v_pk_mul_f32 v[150:151], v[150:151], v[158:159]
	v_lshlrev_b32_e32 v158, 16, v240
	v_and_b32_e32 v159, 0xffff0000, v240
	v_pk_fma_f32 v[158:159], v[100:101], v[158:159], v[96:97]
	v_lshlrev_b32_e32 v160, 16, v241
	v_and_b32_e32 v161, 0xffff0000, v241
	v_pk_fma_f32 v[158:159], v[92:93], v[162:163], v[158:159]
	v_lshlrev_b32_e32 v162, 16, v171
	v_pk_fma_f32 v[158:159], v[88:89], v[160:161], v[158:159]
	v_and_b32_e32 v163, 0xffff0000, v171
	v_cvt_pk_bf16_f32 v149, v150, v151
	v_mul_f32_e32 v160, 0xbfb8aa3b, v158
	v_mul_f32_e32 v161, 0xbfb8aa3b, v159
	v_exp_f32_e32 v160, v160
	v_exp_f32_e32 v161, v161
	v_add_f32_e32 v160, 1.0, v160
	v_add_f32_e32 v161, 1.0, v161
	v_rcp_f32_e32 v160, v160
	v_rcp_f32_e32 v161, v161
	s_nop 0
	v_pk_mul_f32 v[158:159], v[158:159], v[160:161]
	s_nop 0
	v_pk_mul_f32 v[144:145], v[144:145], v[158:159]
	v_lshlrev_b32_e32 v158, 16, v242
	v_and_b32_e32 v159, 0xffff0000, v242
	v_pk_fma_f32 v[158:159], v[102:103], v[158:159], v[98:99]
	v_lshlrev_b32_e32 v160, 16, v243
	v_and_b32_e32 v161, 0xffff0000, v243
	v_pk_fma_f32 v[158:159], v[94:95], v[162:163], v[158:159]
	v_mov_b32_dpp v163, v152 row_ror:15 row_mask:0xf bank_mask:0xf
	v_pk_fma_f32 v[158:159], v[90:91], v[160:161], v[158:159]
	v_cvt_pk_bf16_f32 v150, v144, v145
	v_mad_i64_i32 v[144:145], s[2:3], v233, s26, v[172:173]
	v_mul_f32_e32 v160, 0xbfb8aa3b, v158
	v_mul_f32_e32 v161, 0xbfb8aa3b, v159
	v_exp_f32_e32 v160, v160
	v_exp_f32_e32 v161, v161
	v_cndmask_b32_e64 v233, v237, v170, s[6:7]
	v_or_b32_e32 v162, 32, v226
	v_add_f32_e32 v160, 1.0, v160
	v_add_f32_e32 v161, 1.0, v161
	v_rcp_f32_e32 v160, v160
	v_rcp_f32_e32 v161, v161
	s_nop 0
	v_pk_mul_f32 v[158:159], v[158:159], v[160:161]
	s_nop 0
	v_pk_mul_f32 v[146:147], v[146:147], v[158:159]
	v_mov_b32_dpp v158, v164 row_ror:1 row_mask:0xf bank_mask:0xf
	v_cvt_pk_bf16_f32 v151, v146, v147
	v_lshl_add_u64 v[146:147], v[144:145], 0, v[204:205]
	global_store_dwordx4 v[146:147], v[148:151], off
	v_mov_b32_dpp v159, v165 row_ror:1 row_mask:0xf bank_mask:0xf
	v_cndmask_b32_e64 v145, v158, v174, s[4:5]
	v_lshlrev_b32_e32 v144, 16, v145
	v_and_b32_e32 v145, 0xffff0000, v145
	v_cndmask_b32_e64 v149, v234, v163, s[6:7]
	v_pk_fma_f32 v[144:145], v[120:121], v[144:145], v[116:117]
	v_lshlrev_b32_e32 v150, 16, v164
	v_and_b32_e32 v151, 0xffff0000, v164
	v_lshlrev_b32_e32 v148, 16, v149
	v_and_b32_e32 v149, 0xffff0000, v149
	v_pk_fma_f32 v[144:145], v[112:113], v[150:151], v[144:145]
	v_cndmask_b32_e64 v171, v159, v175, s[4:5]
	v_pk_fma_f32 v[144:145], v[108:109], v[148:149], v[144:145]
	v_cndmask_b32_e64 v174, v235, v168, s[6:7]
	v_lshlrev_b32_e32 v150, 16, v165
	v_mul_f32_e32 v148, 0xbfb8aa3b, v144
	v_mul_f32_e32 v149, 0xbfb8aa3b, v145
	v_exp_f32_e32 v148, v148
	v_exp_f32_e32 v149, v149
	v_and_b32_e32 v151, 0xffff0000, v165
	v_mov_b32_dpp v160, v166 row_ror:1 row_mask:0xf bank_mask:0xf
	v_add_f32_e32 v148, 1.0, v148
	v_add_f32_e32 v149, 1.0, v149
	v_rcp_f32_e32 v148, v148
	v_rcp_f32_e32 v149, v149
	v_cndmask_b32_e64 v175, v160, v231, s[4:5]
	v_cndmask_b32_e64 v231, v236, v169, s[6:7]
	v_mov_b32_dpp v161, v167 row_ror:1 row_mask:0xf bank_mask:0xf
	v_pk_mul_f32 v[144:145], v[144:145], v[148:149]
	v_lshlrev_b32_e32 v148, 16, v174
	v_pk_mul_f32 v[140:141], v[140:141], v[144:145]
	v_lshlrev_b32_e32 v144, 16, v171
	v_and_b32_e32 v145, 0xffff0000, v171
	v_pk_fma_f32 v[144:145], v[122:123], v[144:145], v[118:119]
	v_and_b32_e32 v149, 0xffff0000, v174
	v_pk_fma_f32 v[144:145], v[114:115], v[150:151], v[144:145]
	v_lshlrev_b32_e32 v150, 16, v166
	v_pk_fma_f32 v[144:145], v[110:111], v[148:149], v[144:145]
	v_and_b32_e32 v151, 0xffff0000, v166
	v_cndmask_b32_e64 v232, v161, v232, s[4:5]
	v_mul_f32_e32 v148, 0xbfb8aa3b, v144
	v_mul_f32_e32 v149, 0xbfb8aa3b, v145
	v_exp_f32_e32 v148, v148
	v_exp_f32_e32 v149, v149
	v_or_b32_e32 v164, s12, v221
	v_add_f32_e32 v148, 1.0, v148
	v_add_f32_e32 v149, 1.0, v149
	v_rcp_f32_e32 v148, v148
	v_rcp_f32_e32 v149, v149
	s_nop 0
	v_pk_mul_f32 v[144:145], v[144:145], v[148:149]
	s_nop 0
	v_pk_mul_f32 v[142:143], v[142:143], v[144:145]
	v_lshlrev_b32_e32 v144, 16, v175
	v_and_b32_e32 v145, 0xffff0000, v175
	v_pk_fma_f32 v[144:145], v[100:101], v[144:145], v[96:97]
	v_lshlrev_b32_e32 v148, 16, v231
	v_and_b32_e32 v149, 0xffff0000, v231
	v_pk_fma_f32 v[144:145], v[92:93], v[150:151], v[144:145]
	v_lshlrev_b32_e32 v150, 16, v167
	v_pk_fma_f32 v[144:145], v[88:89], v[148:149], v[144:145]
	v_and_b32_e32 v151, 0xffff0000, v167
	s_nop 0
	v_mul_f32_e32 v148, 0xbfb8aa3b, v144
	v_mul_f32_e32 v149, 0xbfb8aa3b, v145
	v_exp_f32_e32 v148, v148
	v_exp_f32_e32 v149, v149
	v_add_f32_e32 v148, 1.0, v148
	v_add_f32_e32 v149, 1.0, v149
	v_rcp_f32_e32 v148, v148
	v_rcp_f32_e32 v149, v149
	s_nop 0
	v_pk_mul_f32 v[144:145], v[144:145], v[148:149]
	s_nop 0
	v_pk_mul_f32 v[144:145], v[136:137], v[144:145]
	v_lshlrev_b32_e32 v136, 16, v232
	v_and_b32_e32 v137, 0xffff0000, v232
	v_pk_fma_f32 v[136:137], v[102:103], v[136:137], v[98:99]
	v_lshlrev_b32_e32 v148, 16, v233
	v_and_b32_e32 v149, 0xffff0000, v233
	v_pk_fma_f32 v[136:137], v[94:95], v[150:151], v[136:137]
	v_cndmask_b32_e64 v150, v169, v228, s[6:7]
	v_pk_fma_f32 v[136:137], v[90:91], v[148:149], v[136:137]
	s_nop 0
	s_nop 0
	v_mul_f32_e32 v148, 0xbfb8aa3b, v136
	v_mul_f32_e32 v149, 0xbfb8aa3b, v137
	v_exp_f32_e32 v148, v148
	v_exp_f32_e32 v149, v149
	v_add_f32_e32 v148, 1.0, v148
	v_add_f32_e32 v149, 1.0, v149
	v_rcp_f32_e32 v148, v148
	v_rcp_f32_e32 v149, v149
	s_nop 0
	v_pk_mul_f32 v[136:137], v[136:137], v[148:149]
	s_nop 0
	v_pk_mul_f32 v[148:149], v[138:139], v[136:137]
	v_cvt_pk_bf16_f32 v136, v140, v141
	v_mad_i64_i32 v[140:141], s[2:3], v162, s26, v[172:173]
	v_cvt_pk_bf16_f32 v137, v142, v143
	v_cvt_pk_bf16_f32 v138, v144, v145
	v_cvt_pk_bf16_f32 v139, v148, v149
	v_lshl_add_u64 v[148:149], v[140:141], 0, v[204:205]
	global_store_dwordx4 v[148:149], v[136:139], off
	ds_bpermute_b32 v136, v193, v152
	ds_bpermute_b32 v137, v193, v153
	v_mov_b32_dpp v138, v154 row_ror:1 row_mask:0xf bank_mask:0xf
	v_mov_b32_dpp v139, v155 row_ror:1 row_mask:0xf bank_mask:0xf
	v_cndmask_b32_e64 v141, v163, v230, s[6:7]
	s_waitcnt lgkmcnt(0)
	v_cndmask_b32_e64 v140, v136, v158, s[4:5]
	v_cndmask_b32_e64 v143, v137, v159, s[4:5]
	v_lshlrev_b32_e32 v136, 16, v140
	v_and_b32_e32 v137, 0xffff0000, v140
	v_cndmask_b32_e64 v145, v138, v160, s[4:5]
	v_cndmask_b32_e64 v151, v139, v161, s[4:5]
	v_lshlrev_b32_e32 v138, 16, v141
	v_and_b32_e32 v139, 0xffff0000, v141
	v_pk_fma_f32 v[136:137], v[120:121], v[136:137], v[116:117]
	v_lshlrev_b32_e32 v140, 16, v152
	v_and_b32_e32 v141, 0xffff0000, v152
	v_pk_fma_f32 v[136:137], v[112:113], v[140:141], v[136:137]
	v_cndmask_b32_e64 v144, v168, v229, s[6:7]
	v_pk_fma_f32 v[136:137], v[108:109], v[138:139], v[136:137]
	v_lshlrev_b32_e32 v140, 16, v153
	v_and_b32_e32 v141, 0xffff0000, v153
	v_mul_f32_e32 v138, 0xbfb8aa3b, v136
	v_mul_f32_e32 v139, 0xbfb8aa3b, v137
	v_exp_f32_e32 v138, v138
	v_exp_f32_e32 v139, v139
	v_cndmask_b32_e64 v158, v170, v227, s[6:7]
	v_or_b32_e32 v142, 48, v226
	v_add_f32_e32 v138, 1.0, v138
	v_add_f32_e32 v139, 1.0, v139
	v_rcp_f32_e32 v138, v138
	v_rcp_f32_e32 v139, v139
	s_nop 0
	v_pk_mul_f32 v[136:137], v[136:137], v[138:139]
	s_nop 0
	v_pk_mul_f32 v[132:133], v[132:133], v[136:137]
	v_lshlrev_b32_e32 v136, 16, v143
	v_and_b32_e32 v137, 0xffff0000, v143
	v_pk_fma_f32 v[136:137], v[122:123], v[136:137], v[118:119]
	v_lshlrev_b32_e32 v138, 16, v144
	v_and_b32_e32 v139, 0xffff0000, v144
	v_pk_fma_f32 v[136:137], v[114:115], v[140:141], v[136:137]
	v_lshlrev_b32_e32 v140, 16, v154
	v_pk_fma_f32 v[136:137], v[110:111], v[138:139], v[136:137]
	v_and_b32_e32 v141, 0xffff0000, v154
	s_nop 0
	v_mul_f32_e32 v138, 0xbfb8aa3b, v136
	v_mul_f32_e32 v139, 0xbfb8aa3b, v137
	v_exp_f32_e32 v138, v138
	v_exp_f32_e32 v139, v139
	v_add_f32_e32 v138, 1.0, v138
	v_add_f32_e32 v139, 1.0, v139
	v_rcp_f32_e32 v138, v138
	v_rcp_f32_e32 v139, v139
	s_nop 0
	v_pk_mul_f32 v[136:137], v[136:137], v[138:139]
	s_nop 0
	v_pk_mul_f32 v[134:135], v[134:135], v[136:137]
	v_lshlrev_b32_e32 v136, 16, v145
	v_and_b32_e32 v137, 0xffff0000, v145
	v_pk_fma_f32 v[136:137], v[100:101], v[136:137], v[96:97]
	v_lshlrev_b32_e32 v138, 16, v150
	v_and_b32_e32 v139, 0xffff0000, v150
	v_pk_fma_f32 v[136:137], v[92:93], v[140:141], v[136:137]
	v_lshlrev_b32_e32 v140, 16, v155
	v_pk_fma_f32 v[136:137], v[88:89], v[138:139], v[136:137]
	v_and_b32_e32 v141, 0xffff0000, v155
	s_nop 0
	v_mul_f32_e32 v138, 0xbfb8aa3b, v136
	v_mul_f32_e32 v139, 0xbfb8aa3b, v137
	v_exp_f32_e32 v138, v138
	v_exp_f32_e32 v139, v139
	v_add_f32_e32 v138, 1.0, v138
	v_add_f32_e32 v139, 1.0, v139
	v_rcp_f32_e32 v138, v138
	v_rcp_f32_e32 v139, v139
	s_nop 0
	v_pk_mul_f32 v[136:137], v[136:137], v[138:139]
	s_nop 0
	v_pk_mul_f32 v[136:137], v[128:129], v[136:137]
	v_lshlrev_b32_e32 v128, 16, v151
	v_and_b32_e32 v129, 0xffff0000, v151
	v_pk_fma_f32 v[128:129], v[102:103], v[128:129], v[98:99]
	v_lshlrev_b32_e32 v138, 16, v158
	v_and_b32_e32 v139, 0xffff0000, v158
	v_pk_fma_f32 v[128:129], v[94:95], v[140:141], v[128:129]
	s_nop 0
	v_pk_fma_f32 v[128:129], v[90:91], v[138:139], v[128:129]
	s_nop 0
	s_nop 0
	v_mul_f32_e32 v138, 0xbfb8aa3b, v128
	v_mul_f32_e32 v139, 0xbfb8aa3b, v129
	v_exp_f32_e32 v138, v138
	v_exp_f32_e32 v139, v139
	v_add_f32_e32 v138, 1.0, v138
	v_add_f32_e32 v139, 1.0, v139
	v_rcp_f32_e32 v138, v138
	v_rcp_f32_e32 v139, v139
	s_nop 0
	v_pk_mul_f32 v[128:129], v[128:129], v[138:139]
	s_nop 0
	v_pk_mul_f32 v[138:139], v[130:131], v[128:129]
	v_cvt_pk_bf16_f32 v128, v132, v133
	v_mad_i64_i32 v[132:133], s[2:3], v142, s26, v[172:173]
	v_cvt_pk_bf16_f32 v129, v134, v135
	v_cvt_pk_bf16_f32 v130, v136, v137
	v_cvt_pk_bf16_f32 v131, v138, v139
	v_lshl_add_u64 v[144:145], v[132:133], 0, v[204:205]
	global_store_dwordx4 v[144:145], v[128:131], off
	s_nop 1
	v_mad_i64_i32 v[128:129], s[2:3], v164, s26, v[208:209]
	v_lshl_add_u64 v[150:151], v[128:129], 0, v[204:205]
	v_add_co_u32_e32 v152, vcc, s21, v150
	s_mul_hi_i32 s2, s12, 0x2c00
	s_nop 0
	v_addc_co_u32_e32 v153, vcc, 0, v151, vcc
	v_add_co_u32_e32 v154, vcc, s22, v150
	global_load_dwordx4 v[140:143], v[150:151], off
	global_load_dwordx4 v[136:139], v[152:153], off
	v_addc_co_u32_e32 v155, vcc, 0, v151, vcc
	v_add_co_u32_e32 v158, vcc, s23, v150
	s_cselect_b64 s[22:23], -1, 0
	s_add_i32 s1, s1, 0x160000
	s_add_u32 s0, s10, s1
	s_addc_u32 s1, s11, s2
	s_and_b64 s[2:3], s[22:23], exec
	v_addc_co_u32_e32 v159, vcc, 0, v151, vcc
	s_cselect_b32 s2, 0, 0xffffd400
	s_cselect_b32 s3, 0, -1
	s_cmp_eq_u32 s15, s13
	s_cselect_b64 vcc, -1, 0
	v_lshl_add_u64 v[160:161], s[0:1], 0, v[204:205]
	s_and_b64 s[0:1], vcc, exec
	s_cselect_b32 s72, 0, 0xb0000
	v_lshl_add_u64 v[162:163], v[160:161], 0, s[2:3]
	v_lshl_add_u64 v[160:161], v[160:161], 0, s[72:73]
	global_load_dwordx4 v[166:169], v[162:163], off
	global_load_dwordx4 v[226:229], v[160:161], off
	global_load_dwordx4 v[132:135], v[154:155], off
	global_load_dwordx4 v[128:131], v[158:159], off
	s_waitcnt vmcnt(5)
	v_mov_b32_dpp v175, v140 row_ror:15 row_mask:0xf bank_mask:0xf
	v_mov_b32_dpp v208, v141 row_ror:15 row_mask:0xf bank_mask:0xf
	v_mov_b32_dpp v209, v142 row_ror:15 row_mask:0xf bank_mask:0xf
	s_waitcnt vmcnt(4)
	v_mov_b32_dpp v231, v136 row_ror:15 row_mask:0xf bank_mask:0xf
	v_mov_b32_dpp v232, v137 row_ror:15 row_mask:0xf bank_mask:0xf
	v_mov_b32_dpp v233, v138 row_ror:15 row_mask:0xf bank_mask:0xf
	v_mov_b32_dpp v230, v143 row_ror:15 row_mask:0xf bank_mask:0xf
	v_mov_b32_dpp v234, v139 row_ror:15 row_mask:0xf bank_mask:0xf
	v_cndmask_b32_e64 v175, v175, v231, s[6:7]
	v_cndmask_b32_e64 v237, v208, v232, s[6:7]
	v_cndmask_b32_e64 v239, v209, v233, s[6:7]
	v_lshlrev_b32_e32 v208, 16, v140
	v_and_b32_e32 v209, 0xffff0000, v140
	v_cndmask_b32_e64 v230, v230, v234, s[6:7]
	s_waitcnt vmcnt(3)
	v_cndmask_b32_e64 v170, v168, 0, s[22:23]
	s_waitcnt vmcnt(2)
	v_cndmask_b32_e64 v168, v226, 0, vcc
	v_mov_b32_dpp v226, v140 row_ror:1 row_mask:0xf bank_mask:0xf
	v_cndmask_b32_e64 v171, v167, 0, s[22:23]
	v_cndmask_b32_e64 v174, v166, 0, s[22:23]
	v_cndmask_b32_e64 v166, v228, 0, vcc
	v_cndmask_b32_e64 v167, v227, 0, vcc
	v_mov_b32_dpp v227, v141 row_ror:1 row_mask:0xf bank_mask:0xf
	v_mov_b32_dpp v228, v142 row_ror:1 row_mask:0xf bank_mask:0xf
	v_cndmask_b32_e64 v235, v226, v174, s[4:5]
	v_lshlrev_b32_e32 v174, 16, v175
	v_and_b32_e32 v175, 0xffff0000, v175
	v_cndmask_b32_e64 v236, v227, v171, s[4:5]
	v_cndmask_b32_e64 v238, v228, v170, s[4:5]
	v_lshlrev_b32_e32 v170, 16, v235
	v_and_b32_e32 v171, 0xffff0000, v235
	v_pk_fma_f32 v[170:171], v[120:121], v[170:171], v[116:117]
	v_cndmask_b32_e64 v165, v229, 0, vcc
	v_pk_fma_f32 v[170:171], v[112:113], v[208:209], v[170:171]
	v_mov_b32_dpp v229, v143 row_ror:1 row_mask:0xf bank_mask:0xf
	v_pk_fma_f32 v[170:171], v[108:109], v[174:175], v[170:171]
	v_cndmask_b32_e64 v169, v169, 0, s[22:23]
	v_cndmask_b32_e64 v169, v229, v169, s[4:5]
	v_mul_f32_e32 v140, 0xbfb8aa3b, v170
	v_exp_f32_e32 v140, v140
	s_nop 0
	v_add_f32_e32 v140, 1.0, v140
	v_rcp_f32_e32 v174, v140
	v_mul_f32_e32 v140, 0xbfb8aa3b, v171
	v_exp_f32_e32 v140, v140
	s_nop 0
	v_add_f32_e32 v140, 1.0, v140
	v_rcp_f32_e32 v175, v140
	v_lshlrev_b32_e32 v140, 16, v141
	v_and_b32_e32 v141, 0xffff0000, v141
	v_pk_mul_f32 v[170:171], v[170:171], v[174:175]
	s_nop 0
	v_pk_mul_f32 v[124:125], v[124:125], v[170:171]
	v_lshlrev_b32_e32 v170, 16, v236
	v_and_b32_e32 v171, 0xffff0000, v236
	v_pk_mul_f32 v[170:171], v[122:123], v[170:171]
	v_lshlrev_b32_e32 v174, 16, v237
	v_and_b32_e32 v175, 0xffff0000, v237
	v_pk_fma_f32 v[140:141], v[114:115], v[140:141], v[170:171]
	s_nop 0
	v_pk_fma_f32 v[140:141], v[110:111], v[174:175], v[140:141]
	v_lshlrev_b32_e32 v174, 16, v142
	v_pk_add_f32 v[140:141], v[118:119], v[140:141]
	v_and_b32_e32 v175, 0xffff0000, v142
	v_mul_f32_e32 v170, 0xbfb8aa3b, v140
	v_mul_f32_e32 v171, 0xbfb8aa3b, v141
	v_exp_f32_e32 v170, v170
	v_exp_f32_e32 v171, v171
	v_add_f32_e32 v170, 1.0, v170
	v_add_f32_e32 v171, 1.0, v171
	v_rcp_f32_e32 v170, v170
	v_rcp_f32_e32 v171, v171
	s_nop 0
	v_pk_mul_f32 v[140:141], v[140:141], v[170:171]
	s_nop 0
	v_pk_mul_f32 v[126:127], v[126:127], v[140:141]
	v_lshlrev_b32_e32 v140, 16, v238
	v_and_b32_e32 v141, 0xffff0000, v238
	v_pk_fma_f32 v[140:141], v[100:101], v[140:141], v[96:97]
	v_lshlrev_b32_e32 v170, 16, v239
	v_and_b32_e32 v171, 0xffff0000, v239
	v_pk_fma_f32 v[140:141], v[92:93], v[174:175], v[140:141]
	s_waitcnt vmcnt(1)
	v_mov_b32_dpp v174, v134 row_ror:15 row_mask:0xf bank_mask:0xf
	v_pk_fma_f32 v[140:141], v[88:89], v[170:171], v[140:141]
	v_mov_b32_dpp v175, v135 row_ror:15 row_mask:0xf bank_mask:0xf
	s_nop 0
	v_mul_f32_e32 v142, 0xbfb8aa3b, v140
	v_exp_f32_e32 v142, v142
	s_nop 0
	v_add_f32_e32 v142, 1.0, v142
	v_rcp_f32_e32 v170, v142
	v_mul_f32_e32 v142, 0xbfb8aa3b, v141
	v_exp_f32_e32 v142, v142
	s_nop 0
	v_add_f32_e32 v142, 1.0, v142
	v_rcp_f32_e32 v171, v142
	v_lshlrev_b32_e32 v142, 16, v143
	v_and_b32_e32 v143, 0xffff0000, v143
	v_pk_mul_f32 v[140:141], v[140:141], v[170:171]
	s_nop 0
	v_pk_mul_f32 v[140:141], v[104:105], v[140:141]
	v_lshlrev_b32_e32 v104, 16, v169
	v_and_b32_e32 v105, 0xffff0000, v169
	v_pk_fma_f32 v[104:105], v[102:103], v[104:105], v[98:99]
	v_lshlrev_b32_e32 v170, 16, v230
	v_and_b32_e32 v171, 0xffff0000, v230
	v_pk_fma_f32 v[104:105], v[94:95], v[142:143], v[104:105]
	v_or_b32_e32 v169, 16, v164
	v_pk_fma_f32 v[104:105], v[90:91], v[170:171], v[104:105]
	v_mov_b32_dpp v170, v132 row_ror:15 row_mask:0xf bank_mask:0xf
	v_mov_b32_dpp v171, v133 row_ror:15 row_mask:0xf bank_mask:0xf
	v_mul_f32_e32 v142, 0xbfb8aa3b, v104
	v_mul_f32_e32 v143, 0xbfb8aa3b, v105
	v_exp_f32_e32 v142, v142
	v_exp_f32_e32 v143, v143
	v_cndmask_b32_e64 v209, v232, v171, s[6:7]
	v_add_f32_e32 v142, 1.0, v142
	v_add_f32_e32 v143, 1.0, v143
	v_rcp_f32_e32 v142, v142
	v_rcp_f32_e32 v143, v143
	s_nop 0
	v_pk_mul_f32 v[104:105], v[104:105], v[142:143]
	s_nop 0
	v_pk_mul_f32 v[142:143], v[106:107], v[104:105]
	v_cvt_pk_bf16_f32 v106, v140, v141
	v_mov_b32_dpp v140, v136 row_ror:1 row_mask:0xf bank_mask:0xf
	v_cvt_pk_bf16_f32 v104, v124, v125
	v_mad_i64_i32 v[124:125], s[0:1], v164, s26, v[172:173]
	v_cvt_pk_bf16_f32 v105, v126, v127
	v_cvt_pk_bf16_f32 v107, v142, v143
	v_lshl_add_u64 v[124:125], v[124:125], 0, v[204:205]
	global_store_dwordx4 v[124:125], v[104:107], off
	v_lshlrev_b32_e32 v126, 16, v136
	v_and_b32_e32 v127, 0xffff0000, v136
	v_cndmask_b32_e64 v105, v140, v226, s[4:5]
	v_lshlrev_b32_e32 v104, 16, v105
	v_and_b32_e32 v105, 0xffff0000, v105
	v_cndmask_b32_e64 v107, v231, v170, s[6:7]
	v_pk_fma_f32 v[104:105], v[120:121], v[104:105], v[116:117]
	v_lshlrev_b32_e32 v106, 16, v107
	v_and_b32_e32 v107, 0xffff0000, v107
	v_pk_fma_f32 v[104:105], v[112:113], v[126:127], v[104:105]
	v_mov_b32_dpp v141, v137 row_ror:1 row_mask:0xf bank_mask:0xf
	v_pk_fma_f32 v[104:105], v[108:109], v[106:107], v[104:105]
	v_lshlrev_b32_e32 v126, 16, v137
	v_and_b32_e32 v127, 0xffff0000, v137
	v_mul_f32_e32 v106, 0xbfb8aa3b, v104
	v_mul_f32_e32 v107, 0xbfb8aa3b, v105
	v_exp_f32_e32 v106, v106
	v_exp_f32_e32 v107, v107
	v_cndmask_b32_e64 v208, v141, v227, s[4:5]
	v_mov_b32_dpp v142, v138 row_ror:1 row_mask:0xf bank_mask:0xf
	v_add_f32_e32 v106, 1.0, v106
	v_add_f32_e32 v107, 1.0, v107
	v_rcp_f32_e32 v106, v106
	v_rcp_f32_e32 v107, v107
	v_cndmask_b32_e64 v226, v142, v228, s[4:5]
	v_cndmask_b32_e64 v227, v233, v174, s[6:7]
	v_mov_b32_dpp v143, v139 row_ror:1 row_mask:0xf bank_mask:0xf
	v_pk_mul_f32 v[104:105], v[104:105], v[106:107]
	v_lshlrev_b32_e32 v106, 16, v209
	v_pk_mul_f32 v[84:85], v[84:85], v[104:105]
	v_lshlrev_b32_e32 v104, 16, v208
	v_and_b32_e32 v105, 0xffff0000, v208
	v_pk_fma_f32 v[104:105], v[122:123], v[104:105], v[118:119]
	v_and_b32_e32 v107, 0xffff0000, v209
	v_pk_fma_f32 v[104:105], v[114:115], v[126:127], v[104:105]
	v_lshlrev_b32_e32 v126, 16, v138
	v_pk_fma_f32 v[104:105], v[110:111], v[106:107], v[104:105]
	v_and_b32_e32 v127, 0xffff0000, v138
	v_cndmask_b32_e64 v228, v143, v229, s[4:5]
	v_mul_f32_e32 v106, 0xbfb8aa3b, v104
	v_mul_f32_e32 v107, 0xbfb8aa3b, v105
	v_exp_f32_e32 v106, v106
	v_exp_f32_e32 v107, v107
	v_cndmask_b32_e64 v229, v234, v175, s[6:7]
	s_waitcnt vmcnt(1)
	v_mov_b32_dpp v136, v129 row_ror:15 row_mask:0xf bank_mask:0xf
	v_add_f32_e32 v106, 1.0, v106
	v_add_f32_e32 v107, 1.0, v107
	v_rcp_f32_e32 v106, v106
	v_rcp_f32_e32 v107, v107
	v_mov_b32_dpp v137, v130 row_ror:15 row_mask:0xf bank_mask:0xf
	v_mov_b32_dpp v138, v131 row_ror:15 row_mask:0xf bank_mask:0xf
	v_pk_mul_f32 v[104:105], v[104:105], v[106:107]
	s_nop 0
	v_pk_mul_f32 v[86:87], v[86:87], v[104:105]
	v_lshlrev_b32_e32 v104, 16, v226
	v_and_b32_e32 v105, 0xffff0000, v226
	v_pk_fma_f32 v[104:105], v[100:101], v[104:105], v[96:97]
	v_lshlrev_b32_e32 v106, 16, v227
	v_and_b32_e32 v107, 0xffff0000, v227
	v_pk_fma_f32 v[104:105], v[92:93], v[126:127], v[104:105]
	v_lshlrev_b32_e32 v126, 16, v139
	v_pk_fma_f32 v[104:105], v[88:89], v[106:107], v[104:105]
	v_and_b32_e32 v127, 0xffff0000, v139
	s_nop 0
	v_mul_f32_e32 v106, 0xbfb8aa3b, v104
	v_mul_f32_e32 v107, 0xbfb8aa3b, v105
	v_exp_f32_e32 v106, v106
	v_exp_f32_e32 v107, v107
	v_add_f32_e32 v106, 1.0, v106
	v_add_f32_e32 v107, 1.0, v107
	v_rcp_f32_e32 v106, v106
	v_rcp_f32_e32 v107, v107
	s_nop 0
	v_pk_mul_f32 v[104:105], v[104:105], v[106:107]
	s_nop 0
	v_pk_mul_f32 v[104:105], v[80:81], v[104:105]
	v_lshlrev_b32_e32 v80, 16, v228
	v_and_b32_e32 v81, 0xffff0000, v228
	v_pk_fma_f32 v[80:81], v[102:103], v[80:81], v[98:99]
	v_lshlrev_b32_e32 v106, 16, v229
	v_and_b32_e32 v107, 0xffff0000, v229
	v_pk_fma_f32 v[80:81], v[94:95], v[126:127], v[80:81]
	s_nop 0
	v_pk_fma_f32 v[80:81], v[90:91], v[106:107], v[80:81]
	s_nop 0
	s_nop 0
	v_mul_f32_e32 v106, 0xbfb8aa3b, v80
	v_mul_f32_e32 v107, 0xbfb8aa3b, v81
	v_exp_f32_e32 v106, v106
	v_exp_f32_e32 v107, v107
	v_add_f32_e32 v106, 1.0, v106
	v_add_f32_e32 v107, 1.0, v107
	v_rcp_f32_e32 v106, v106
	v_rcp_f32_e32 v107, v107
	s_nop 0
	v_pk_mul_f32 v[80:81], v[80:81], v[106:107]
	s_nop 0
	v_pk_mul_f32 v[106:107], v[82:83], v[80:81]
	v_cvt_pk_bf16_f32 v81, v86, v87
	v_mov_b32_dpp v86, v132 row_ror:1 row_mask:0xf bank_mask:0xf
	v_cvt_pk_bf16_f32 v83, v106, v107
	v_mov_b32_dpp v107, v128 row_ror:15 row_mask:0xf bank_mask:0xf
	v_cvt_pk_bf16_f32 v80, v84, v85
	v_mad_i64_i32 v[84:85], s[0:1], v169, s26, v[172:173]
	v_cvt_pk_bf16_f32 v82, v104, v105
	v_lshl_add_u64 v[126:127], v[84:85], 0, v[204:205]
	global_store_dwordx4 v[126:127], v[80:83], off
	v_lshlrev_b32_e32 v84, 16, v132
	v_and_b32_e32 v85, 0xffff0000, v132
	v_cndmask_b32_e64 v81, v86, v140, s[4:5]
	v_lshlrev_b32_e32 v80, 16, v81
	v_and_b32_e32 v81, 0xffff0000, v81
	v_cndmask_b32_e64 v83, v170, v107, s[6:7]
	v_pk_fma_f32 v[80:81], v[120:121], v[80:81], v[116:117]
	v_lshlrev_b32_e32 v82, 16, v83
	v_and_b32_e32 v83, 0xffff0000, v83
	v_pk_fma_f32 v[80:81], v[112:113], v[84:85], v[80:81]
	v_mov_b32_dpp v87, v133 row_ror:1 row_mask:0xf bank_mask:0xf
	v_pk_fma_f32 v[80:81], v[108:109], v[82:83], v[80:81]
	v_cndmask_b32_e64 v140, v171, v136, s[6:7]
	v_lshlrev_b32_e32 v84, 16, v133
	v_mul_f32_e32 v82, 0xbfb8aa3b, v80
	v_mul_f32_e32 v83, 0xbfb8aa3b, v81
	v_exp_f32_e32 v82, v82
	v_exp_f32_e32 v83, v83
	v_cndmask_b32_e64 v139, v87, v141, s[4:5]
	v_and_b32_e32 v85, 0xffff0000, v133
	v_add_f32_e32 v82, 1.0, v82
	v_add_f32_e32 v83, 1.0, v83
	v_rcp_f32_e32 v82, v82
	v_rcp_f32_e32 v83, v83
	v_mov_b32_dpp v104, v134 row_ror:1 row_mask:0xf bank_mask:0xf
	v_mov_b32_dpp v105, v135 row_ror:1 row_mask:0xf bank_mask:0xf
	v_cndmask_b32_e64 v169, v175, v138, s[6:7]
	v_pk_mul_f32 v[80:81], v[80:81], v[82:83]
	v_lshlrev_b32_e32 v82, 16, v140
	v_pk_mul_f32 v[76:77], v[76:77], v[80:81]
	v_lshlrev_b32_e32 v80, 16, v139
	v_and_b32_e32 v81, 0xffff0000, v139
	v_pk_fma_f32 v[80:81], v[122:123], v[80:81], v[118:119]
	v_and_b32_e32 v83, 0xffff0000, v140
	v_pk_fma_f32 v[80:81], v[114:115], v[84:85], v[80:81]
	v_cndmask_b32_e64 v141, v104, v142, s[4:5]
	v_pk_fma_f32 v[80:81], v[110:111], v[82:83], v[80:81]
	v_cndmask_b32_e64 v142, v174, v137, s[6:7]
	v_lshlrev_b32_e32 v84, 16, v134
	v_mul_f32_e32 v82, 0xbfb8aa3b, v80
	v_mul_f32_e32 v83, 0xbfb8aa3b, v81
	v_exp_f32_e32 v82, v82
	v_exp_f32_e32 v83, v83
	v_and_b32_e32 v85, 0xffff0000, v134
	v_cndmask_b32_e64 v143, v105, v143, s[4:5]
	v_add_f32_e32 v82, 1.0, v82
	v_add_f32_e32 v83, 1.0, v83
	v_rcp_f32_e32 v82, v82
	v_rcp_f32_e32 v83, v83
	v_or_b32_e32 v106, 32, v164
	v_pk_mul_f32 v[80:81], v[80:81], v[82:83]
	s_nop 0
	v_pk_mul_f32 v[78:79], v[78:79], v[80:81]
	v_lshlrev_b32_e32 v80, 16, v141
	v_and_b32_e32 v81, 0xffff0000, v141
	v_pk_fma_f32 v[80:81], v[100:101], v[80:81], v[96:97]
	v_lshlrev_b32_e32 v82, 16, v142
	v_and_b32_e32 v83, 0xffff0000, v142
	v_pk_fma_f32 v[80:81], v[92:93], v[84:85], v[80:81]
	v_lshlrev_b32_e32 v84, 16, v135
	v_pk_fma_f32 v[80:81], v[88:89], v[82:83], v[80:81]
	v_and_b32_e32 v85, 0xffff0000, v135
	s_nop 0
	v_mul_f32_e32 v82, 0xbfb8aa3b, v80
	v_mul_f32_e32 v83, 0xbfb8aa3b, v81
	v_exp_f32_e32 v82, v82
	v_exp_f32_e32 v83, v83
	v_add_f32_e32 v82, 1.0, v82
	v_add_f32_e32 v83, 1.0, v83
	v_rcp_f32_e32 v82, v82
	v_rcp_f32_e32 v83, v83
	s_nop 0
	v_pk_mul_f32 v[80:81], v[80:81], v[82:83]
	s_nop 0
	v_pk_mul_f32 v[80:81], v[72:73], v[80:81]
	v_lshlrev_b32_e32 v72, 16, v143
	v_and_b32_e32 v73, 0xffff0000, v143
	v_pk_fma_f32 v[72:73], v[102:103], v[72:73], v[98:99]
	v_lshlrev_b32_e32 v82, 16, v169
	v_and_b32_e32 v83, 0xffff0000, v169
	v_pk_fma_f32 v[72:73], v[94:95], v[84:85], v[72:73]
	v_cndmask_b32_e64 v84, v138, v165, s[6:7]
	v_pk_fma_f32 v[72:73], v[90:91], v[82:83], v[72:73]
	s_nop 0
	s_nop 0
	v_mul_f32_e32 v82, 0xbfb8aa3b, v72
	v_mul_f32_e32 v83, 0xbfb8aa3b, v73
	v_exp_f32_e32 v82, v82
	v_exp_f32_e32 v83, v83
	v_add_f32_e32 v82, 1.0, v82
	v_add_f32_e32 v83, 1.0, v83
	v_rcp_f32_e32 v82, v82
	v_rcp_f32_e32 v83, v83
	s_nop 0
	v_pk_mul_f32 v[72:73], v[72:73], v[82:83]
	s_nop 0
	v_pk_mul_f32 v[82:83], v[74:75], v[72:73]
	v_cvt_pk_bf16_f32 v72, v76, v77
	v_mad_i64_i32 v[76:77], s[0:1], v106, s26, v[172:173]
	v_cvt_pk_bf16_f32 v73, v78, v79
	v_cvt_pk_bf16_f32 v74, v80, v81
	v_cvt_pk_bf16_f32 v75, v82, v83
	v_lshl_add_u64 v[132:133], v[76:77], 0, v[204:205]
	global_store_dwordx4 v[132:133], v[72:75], off
	ds_bpermute_b32 v72, v193, v128
	ds_bpermute_b32 v73, v193, v129
	v_mov_b32_dpp v74, v130 row_ror:1 row_mask:0xf bank_mask:0xf
	v_mov_b32_dpp v75, v131 row_ror:1 row_mask:0xf bank_mask:0xf
	v_cndmask_b32_e64 v77, v107, v168, s[6:7]
	s_waitcnt lgkmcnt(0)
	v_cndmask_b32_e64 v76, v72, v86, s[4:5]
	v_cndmask_b32_e64 v79, v73, v87, s[4:5]
	v_lshlrev_b32_e32 v72, 16, v76
	v_and_b32_e32 v73, 0xffff0000, v76
	v_cndmask_b32_e64 v81, v74, v104, s[4:5]
	v_cndmask_b32_e64 v83, v75, v105, s[4:5]
	v_lshlrev_b32_e32 v74, 16, v77
	v_and_b32_e32 v75, 0xffff0000, v77
	v_pk_fma_f32 v[72:73], v[120:121], v[72:73], v[116:117]
	v_lshlrev_b32_e32 v76, 16, v128
	v_and_b32_e32 v77, 0xffff0000, v128
	v_pk_fma_f32 v[72:73], v[112:113], v[76:77], v[72:73]
	v_cndmask_b32_e64 v80, v136, v167, s[6:7]
	v_pk_fma_f32 v[72:73], v[108:109], v[74:75], v[72:73]
	v_lshlrev_b32_e32 v76, 16, v129
	v_and_b32_e32 v77, 0xffff0000, v129
	v_mul_f32_e32 v74, 0xbfb8aa3b, v72
	v_mul_f32_e32 v75, 0xbfb8aa3b, v73
	v_exp_f32_e32 v74, v74
	v_exp_f32_e32 v75, v75
	v_cndmask_b32_e64 v82, v137, v166, s[6:7]
	v_or_b32_e32 v78, 48, v164
	v_add_f32_e32 v74, 1.0, v74
	v_add_f32_e32 v75, 1.0, v75
	v_rcp_f32_e32 v74, v74
	v_rcp_f32_e32 v75, v75
	s_nop 0
	v_pk_mul_f32 v[72:73], v[72:73], v[74:75]
	s_nop 0
	v_pk_mul_f32 v[68:69], v[68:69], v[72:73]
	v_lshlrev_b32_e32 v72, 16, v79
	v_and_b32_e32 v73, 0xffff0000, v79
	v_pk_fma_f32 v[72:73], v[122:123], v[72:73], v[118:119]
	v_lshlrev_b32_e32 v74, 16, v80
	v_and_b32_e32 v75, 0xffff0000, v80
	v_pk_fma_f32 v[72:73], v[114:115], v[76:77], v[72:73]
	v_lshlrev_b32_e32 v76, 16, v130
	v_pk_fma_f32 v[72:73], v[110:111], v[74:75], v[72:73]
	v_and_b32_e32 v77, 0xffff0000, v130
	s_nop 0
	v_mul_f32_e32 v74, 0xbfb8aa3b, v72
	v_mul_f32_e32 v75, 0xbfb8aa3b, v73
	v_exp_f32_e32 v74, v74
	v_exp_f32_e32 v75, v75
	v_add_f32_e32 v74, 1.0, v74
	v_add_f32_e32 v75, 1.0, v75
	v_rcp_f32_e32 v74, v74
	v_rcp_f32_e32 v75, v75
	s_nop 0
	v_pk_mul_f32 v[72:73], v[72:73], v[74:75]
	s_nop 0
	v_pk_mul_f32 v[70:71], v[70:71], v[72:73]
	v_lshlrev_b32_e32 v72, 16, v81
	v_and_b32_e32 v73, 0xffff0000, v81
	v_pk_fma_f32 v[72:73], v[100:101], v[72:73], v[96:97]
	v_lshlrev_b32_e32 v74, 16, v82
	v_and_b32_e32 v75, 0xffff0000, v82
	v_pk_fma_f32 v[72:73], v[92:93], v[76:77], v[72:73]
	v_lshlrev_b32_e32 v76, 16, v131
	v_pk_fma_f32 v[72:73], v[88:89], v[74:75], v[72:73]
	v_and_b32_e32 v77, 0xffff0000, v131
	s_nop 0
	v_mul_f32_e32 v74, 0xbfb8aa3b, v72
	v_mul_f32_e32 v75, 0xbfb8aa3b, v73
	v_exp_f32_e32 v74, v74
	v_exp_f32_e32 v75, v75
	v_add_f32_e32 v74, 1.0, v74
	v_add_f32_e32 v75, 1.0, v75
	v_rcp_f32_e32 v74, v74
	v_rcp_f32_e32 v75, v75
	s_nop 0
	v_pk_mul_f32 v[72:73], v[72:73], v[74:75]
	s_nop 0
	v_pk_mul_f32 v[72:73], v[64:65], v[72:73]
	v_lshlrev_b32_e32 v64, 16, v83
	v_and_b32_e32 v65, 0xffff0000, v83
	v_pk_fma_f32 v[64:65], v[102:103], v[64:65], v[98:99]
	v_lshlrev_b32_e32 v74, 16, v84
	v_and_b32_e32 v75, 0xffff0000, v84
	v_pk_fma_f32 v[64:65], v[94:95], v[76:77], v[64:65]
	s_nop 0
	v_pk_fma_f32 v[64:65], v[90:91], v[74:75], v[64:65]
	s_nop 0
	s_nop 0
	v_mul_f32_e32 v74, 0xbfb8aa3b, v64
	v_mul_f32_e32 v75, 0xbfb8aa3b, v65
	v_exp_f32_e32 v74, v74
	v_exp_f32_e32 v75, v75
	v_add_f32_e32 v74, 1.0, v74
	v_add_f32_e32 v75, 1.0, v75
	v_rcp_f32_e32 v74, v74
	v_rcp_f32_e32 v75, v75
	s_nop 0
	v_pk_mul_f32 v[64:65], v[64:65], v[74:75]
	s_nop 0
	v_pk_mul_f32 v[74:75], v[66:67], v[64:65]
	v_cvt_pk_bf16_f32 v64, v68, v69
	v_mad_i64_i32 v[68:69], s[0:1], v78, s26, v[172:173]
	v_cvt_pk_bf16_f32 v65, v70, v71
	v_cvt_pk_bf16_f32 v66, v72, v73
	v_cvt_pk_bf16_f32 v67, v74, v75
	v_lshl_add_u64 v[112:113], v[68:69], 0, v[204:205]
	global_store_dwordx4 v[112:113], v[64:67], off
	s_mov_b64 s[0:1], -1
	s_nop 0
	v_or_b32_e32 v64, 0x80, v192
	v_ashrrev_i32_e32 v65, 31, v64
	v_lshlrev_b64 v[64:65], 2, v[64:65]
	v_lshl_add_u64 v[66:67], s[46:47], 0, v[64:65]
	v_lshl_add_u64 v[72:73], s[48:49], 0, v[64:65]
	global_load_dwordx4 v[76:79], v[190:191], off offset:528
	global_load_dwordx4 v[92:95], v[190:191], off offset:512
	global_load_dwordx4 v[68:71], v[66:67], off offset:16
	global_load_dwordx4 v[84:87], v[66:67], off
	s_nop 0
	global_load_dwordx4 v[64:67], v[72:73], off offset:16
	global_load_dwordx4 v[80:83], v[72:73], off
	s_nop 0
	global_load_dwordx4 v[72:75], v[188:189], off offset:528
	global_load_dwordx4 v[88:91], v[188:189], off offset:512
	global_load_dwordx4 v[108:111], v[194:195], off offset:256
	global_load_dwordx4 v[104:107], v[198:199], off offset:256
	global_load_dwordx4 v[100:103], v[200:201], off offset:256
	global_load_dwordx4 v[96:99], v[206:207], off offset:256
	global_load_dwordx4 v[114:117], v[196:197], off offset:256
	global_load_dwordx4 v[118:121], v[202:203], off offset:256
	s_waitcnt vmcnt(5)
	v_mov_b32_dpp v130, v108 row_ror:1 row_mask:0xf bank_mask:0xf
	s_waitcnt vmcnt(4)
	v_mov_b32_dpp v136, v104 row_ror:15 row_mask:0xf bank_mask:0xf
	v_mov_b32_dpp v137, v105 row_ror:15 row_mask:0xf bank_mask:0xf
	v_mov_b32_dpp v134, v110 row_ror:1 row_mask:0xf bank_mask:0xf
	s_waitcnt vmcnt(1)
	v_cndmask_b32_e64 v122, v117, 0, s[62:63]
	v_cndmask_b32_e64 v123, v116, 0, s[62:63]
	s_waitcnt vmcnt(0)
	v_cndmask_b32_e64 v116, v119, 0, s[50:51]
	v_cndmask_b32_e64 v117, v118, 0, s[50:51]
	v_mov_b32_dpp v118, v108 row_ror:15 row_mask:0xf bank_mask:0xf
	v_mov_b32_dpp v119, v109 row_ror:15 row_mask:0xf bank_mask:0xf
	v_mov_b32_dpp v135, v111 row_ror:1 row_mask:0xf bank_mask:0xf
	v_cndmask_b32_e64 v128, v115, 0, s[62:63]
	v_cndmask_b32_e64 v129, v114, 0, s[62:63]
	v_cndmask_b32_e64 v114, v121, 0, s[50:51]
	v_cndmask_b32_e64 v115, v120, 0, s[50:51]
	v_mov_b32_dpp v120, v110 row_ror:15 row_mask:0xf bank_mask:0xf
	v_mov_b32_dpp v121, v111 row_ror:15 row_mask:0xf bank_mask:0xf
	v_mov_b32_dpp v138, v106 row_ror:15 row_mask:0xf bank_mask:0xf
	v_mov_b32_dpp v139, v107 row_ror:15 row_mask:0xf bank_mask:0xf
	v_cndmask_b32_e64 v129, v130, v129, s[4:5]
	v_cndmask_b32_e64 v140, v118, v136, s[6:7]
	v_cndmask_b32_e64 v141, v119, v137, s[6:7]
	v_lshlrev_b32_e32 v118, 16, v129
	v_and_b32_e32 v119, 0xffff0000, v129
	v_cndmask_b32_e64 v142, v134, v123, s[4:5]
	v_cndmask_b32_e64 v164, v135, v122, s[4:5]
	v_pk_fma_f32 v[118:119], v[92:93], v[118:119], v[88:89]
	v_lshlrev_b32_e32 v122, 16, v108
	v_and_b32_e32 v123, 0xffff0000, v108
	v_cndmask_b32_e64 v143, v120, v138, s[6:7]
	v_cndmask_b32_e64 v165, v121, v139, s[6:7]
	v_lshlrev_b32_e32 v120, 16, v140
	v_and_b32_e32 v121, 0xffff0000, v140
	v_pk_fma_f32 v[118:119], v[84:85], v[122:123], v[118:119]
	v_mov_b32_dpp v131, v109 row_ror:1 row_mask:0xf bank_mask:0xf
	v_pk_fma_f32 v[118:119], v[80:81], v[120:121], v[118:119]
	v_cndmask_b32_e64 v128, v131, v128, s[4:5]
	s_nop 0
	v_mul_f32_e32 v108, 0xbfb8aa3b, v118
	v_exp_f32_e32 v108, v108
	s_nop 0
	v_add_f32_e32 v108, 1.0, v108
	v_rcp_f32_e32 v120, v108
	v_mul_f32_e32 v108, 0xbfb8aa3b, v119
	v_exp_f32_e32 v108, v108
	s_nop 0
	v_add_f32_e32 v108, 1.0, v108
	v_rcp_f32_e32 v121, v108
	v_lshlrev_b32_e32 v108, 16, v109
	v_and_b32_e32 v109, 0xffff0000, v109
	v_pk_mul_f32 v[118:119], v[118:119], v[120:121]
	s_nop 0
	v_pk_mul_f32 v[60:61], v[60:61], v[118:119]
	v_lshlrev_b32_e32 v118, 16, v128
	v_and_b32_e32 v119, 0xffff0000, v128
	v_pk_mul_f32 v[118:119], v[94:95], v[118:119]
	v_lshlrev_b32_e32 v120, 16, v141
	v_and_b32_e32 v121, 0xffff0000, v141
	v_pk_fma_f32 v[108:109], v[86:87], v[108:109], v[118:119]
	s_nop 0
	v_pk_fma_f32 v[108:109], v[82:83], v[120:121], v[108:109]
	v_lshlrev_b32_e32 v120, 16, v110
	v_pk_add_f32 v[108:109], v[90:91], v[108:109]
	v_and_b32_e32 v121, 0xffff0000, v110
	v_mul_f32_e32 v118, 0xbfb8aa3b, v108
	v_mul_f32_e32 v119, 0xbfb8aa3b, v109
	v_exp_f32_e32 v118, v118
	v_exp_f32_e32 v119, v119
	v_add_f32_e32 v118, 1.0, v118
	v_add_f32_e32 v119, 1.0, v119
	v_rcp_f32_e32 v118, v118
	v_rcp_f32_e32 v119, v119
	s_nop 0
	v_pk_mul_f32 v[108:109], v[108:109], v[118:119]
	s_nop 0
	v_pk_mul_f32 v[62:63], v[62:63], v[108:109]
	v_lshlrev_b32_e32 v108, 16, v142
	v_and_b32_e32 v109, 0xffff0000, v142
	v_pk_fma_f32 v[108:109], v[76:77], v[108:109], v[72:73]
	v_lshlrev_b32_e32 v118, 16, v143
	v_and_b32_e32 v119, 0xffff0000, v143
	v_pk_fma_f32 v[108:109], v[68:69], v[120:121], v[108:109]
	s_nop 0
	v_pk_fma_f32 v[108:109], v[64:65], v[118:119], v[108:109]
	s_nop 0
	s_nop 0
	v_mul_f32_e32 v110, 0xbfb8aa3b, v108
	v_exp_f32_e32 v110, v110
	s_nop 0
	v_add_f32_e32 v110, 1.0, v110
	v_rcp_f32_e32 v118, v110
	v_mul_f32_e32 v110, 0xbfb8aa3b, v109
	v_exp_f32_e32 v110, v110
	s_nop 0
	v_add_f32_e32 v110, 1.0, v110
	v_rcp_f32_e32 v119, v110
	v_lshlrev_b32_e32 v110, 16, v111
	v_and_b32_e32 v111, 0xffff0000, v111
	v_pk_mul_f32 v[108:109], v[108:109], v[118:119]
	s_nop 0
	v_pk_mul_f32 v[108:109], v[56:57], v[108:109]
	v_lshlrev_b32_e32 v56, 16, v164
	v_and_b32_e32 v57, 0xffff0000, v164
	v_pk_fma_f32 v[56:57], v[78:79], v[56:57], v[74:75]
	v_lshlrev_b32_e32 v118, 16, v165
	v_and_b32_e32 v119, 0xffff0000, v165
	v_pk_fma_f32 v[56:57], v[70:71], v[110:111], v[56:57]
	s_nop 0
	v_pk_fma_f32 v[56:57], v[66:67], v[118:119], v[56:57]
	v_mov_b32_dpp v118, v102 row_ror:15 row_mask:0xf bank_mask:0xf
	v_mov_b32_dpp v119, v103 row_ror:15 row_mask:0xf bank_mask:0xf
	v_mul_f32_e32 v110, 0xbfb8aa3b, v56
	v_mul_f32_e32 v111, 0xbfb8aa3b, v57
	v_exp_f32_e32 v110, v110
	v_exp_f32_e32 v111, v111
	v_cndmask_b32_e64 v123, v138, v118, s[6:7]
	v_cndmask_b32_e64 v129, v139, v119, s[6:7]
	v_add_f32_e32 v110, 1.0, v110
	v_add_f32_e32 v111, 1.0, v111
	v_rcp_f32_e32 v110, v110
	v_rcp_f32_e32 v111, v111
	s_nop 0
	v_pk_mul_f32 v[56:57], v[56:57], v[110:111]
	s_nop 0
	v_pk_mul_f32 v[110:111], v[58:59], v[56:57]
	v_cvt_pk_bf16_f32 v57, v62, v63
	v_mov_b32_dpp v62, v104 row_ror:1 row_mask:0xf bank_mask:0xf
	v_cvt_pk_bf16_f32 v59, v110, v111
	v_mov_b32_dpp v110, v100 row_ror:15 row_mask:0xf bank_mask:0xf
	v_cvt_pk_bf16_f32 v56, v60, v61
	v_cvt_pk_bf16_f32 v58, v108, v109
	global_store_dwordx4 v[156:157], v[56:59], off offset:256
	v_lshlrev_b32_e32 v60, 16, v104
	v_and_b32_e32 v61, 0xffff0000, v104
	v_cndmask_b32_e64 v57, v62, v130, s[4:5]
	v_lshlrev_b32_e32 v56, 16, v57
	v_and_b32_e32 v57, 0xffff0000, v57
	v_cndmask_b32_e64 v59, v136, v110, s[6:7]
	v_pk_fma_f32 v[56:57], v[92:93], v[56:57], v[88:89]
	v_lshlrev_b32_e32 v58, 16, v59
	v_and_b32_e32 v59, 0xffff0000, v59
	v_pk_fma_f32 v[56:57], v[84:85], v[60:61], v[56:57]
	v_mov_b32_dpp v63, v105 row_ror:1 row_mask:0xf bank_mask:0xf
	v_pk_fma_f32 v[56:57], v[80:81], v[58:59], v[56:57]
	v_mov_b32_dpp v111, v101 row_ror:15 row_mask:0xf bank_mask:0xf
	v_lshlrev_b32_e32 v60, 16, v105
	v_mul_f32_e32 v58, 0xbfb8aa3b, v56
	v_mul_f32_e32 v59, 0xbfb8aa3b, v57
	v_exp_f32_e32 v58, v58
	v_exp_f32_e32 v59, v59
	v_cndmask_b32_e64 v120, v63, v131, s[4:5]
	v_cndmask_b32_e64 v121, v137, v111, s[6:7]
	v_add_f32_e32 v58, 1.0, v58
	v_add_f32_e32 v59, 1.0, v59
	v_rcp_f32_e32 v58, v58
	v_rcp_f32_e32 v59, v59
	v_and_b32_e32 v61, 0xffff0000, v105
	v_mov_b32_dpp v108, v106 row_ror:1 row_mask:0xf bank_mask:0xf
	v_mov_b32_dpp v109, v107 row_ror:1 row_mask:0xf bank_mask:0xf
	v_pk_mul_f32 v[56:57], v[56:57], v[58:59]
	v_lshlrev_b32_e32 v58, 16, v121
	v_pk_mul_f32 v[52:53], v[52:53], v[56:57]
	v_lshlrev_b32_e32 v56, 16, v120
	v_and_b32_e32 v57, 0xffff0000, v120
	v_pk_fma_f32 v[56:57], v[94:95], v[56:57], v[90:91]
	v_and_b32_e32 v59, 0xffff0000, v121
	v_pk_fma_f32 v[56:57], v[86:87], v[60:61], v[56:57]
	v_cndmask_b32_e64 v122, v108, v134, s[4:5]
	v_pk_fma_f32 v[56:57], v[82:83], v[58:59], v[56:57]
	v_lshlrev_b32_e32 v60, 16, v106
	v_and_b32_e32 v61, 0xffff0000, v106
	v_mul_f32_e32 v58, 0xbfb8aa3b, v56
	v_mul_f32_e32 v59, 0xbfb8aa3b, v57
	v_exp_f32_e32 v58, v58
	v_exp_f32_e32 v59, v59
	v_cndmask_b32_e64 v128, v109, v135, s[4:5]
	v_add_f32_e32 v58, 1.0, v58
	v_add_f32_e32 v59, 1.0, v59
	v_rcp_f32_e32 v58, v58
	v_rcp_f32_e32 v59, v59
	s_nop 0
	v_pk_mul_f32 v[56:57], v[56:57], v[58:59]
	s_nop 0
	v_pk_mul_f32 v[54:55], v[54:55], v[56:57]
	v_lshlrev_b32_e32 v56, 16, v122
	v_and_b32_e32 v57, 0xffff0000, v122
	v_pk_fma_f32 v[56:57], v[76:77], v[56:57], v[72:73]
	v_lshlrev_b32_e32 v58, 16, v123
	v_and_b32_e32 v59, 0xffff0000, v123
	v_pk_fma_f32 v[56:57], v[68:69], v[60:61], v[56:57]
	v_lshlrev_b32_e32 v60, 16, v107
	v_pk_fma_f32 v[56:57], v[64:65], v[58:59], v[56:57]
	v_and_b32_e32 v61, 0xffff0000, v107
	s_nop 0
	v_mul_f32_e32 v58, 0xbfb8aa3b, v56
	v_mul_f32_e32 v59, 0xbfb8aa3b, v57
	v_exp_f32_e32 v58, v58
	v_exp_f32_e32 v59, v59
	v_add_f32_e32 v58, 1.0, v58
	v_add_f32_e32 v59, 1.0, v59
	v_rcp_f32_e32 v58, v58
	v_rcp_f32_e32 v59, v59
	s_nop 0
	v_pk_mul_f32 v[56:57], v[56:57], v[58:59]
	s_nop 0
	v_pk_mul_f32 v[56:57], v[48:49], v[56:57]
	v_lshlrev_b32_e32 v48, 16, v128
	v_and_b32_e32 v49, 0xffff0000, v128
	v_pk_fma_f32 v[48:49], v[78:79], v[48:49], v[74:75]
	v_lshlrev_b32_e32 v58, 16, v129
	v_and_b32_e32 v59, 0xffff0000, v129
	v_pk_fma_f32 v[48:49], v[70:71], v[60:61], v[48:49]
	v_mov_b32_dpp v60, v98 row_ror:15 row_mask:0xf bank_mask:0xf
	v_pk_fma_f32 v[48:49], v[66:67], v[58:59], v[48:49]
	v_mov_b32_dpp v61, v99 row_ror:15 row_mask:0xf bank_mask:0xf
	v_cndmask_b32_e64 v105, v118, v60, s[6:7]
	v_mul_f32_e32 v58, 0xbfb8aa3b, v48
	v_mul_f32_e32 v59, 0xbfb8aa3b, v49
	v_exp_f32_e32 v58, v58
	v_exp_f32_e32 v59, v59
	v_cndmask_b32_e64 v107, v119, v61, s[6:7]
	v_add_f32_e32 v58, 1.0, v58
	v_add_f32_e32 v59, 1.0, v59
	v_rcp_f32_e32 v58, v58
	v_rcp_f32_e32 v59, v59
	s_nop 0
	v_pk_mul_f32 v[48:49], v[48:49], v[58:59]
	s_nop 0
	v_pk_mul_f32 v[58:59], v[50:51], v[48:49]
	v_cvt_pk_bf16_f32 v49, v54, v55
	v_mov_b32_dpp v54, v100 row_ror:1 row_mask:0xf bank_mask:0xf
	v_cvt_pk_bf16_f32 v51, v58, v59
	v_mov_b32_dpp v58, v96 row_ror:15 row_mask:0xf bank_mask:0xf
	v_cvt_pk_bf16_f32 v48, v52, v53
	v_cvt_pk_bf16_f32 v50, v56, v57
	global_store_dwordx4 v[146:147], v[48:51], off offset:256
	v_lshlrev_b32_e32 v52, 16, v100
	v_and_b32_e32 v53, 0xffff0000, v100
	v_cndmask_b32_e64 v49, v54, v62, s[4:5]
	v_lshlrev_b32_e32 v48, 16, v49
	v_and_b32_e32 v49, 0xffff0000, v49
	v_cndmask_b32_e64 v51, v110, v58, s[6:7]
	v_pk_fma_f32 v[48:49], v[92:93], v[48:49], v[88:89]
	v_lshlrev_b32_e32 v50, 16, v51
	v_and_b32_e32 v51, 0xffff0000, v51
	v_pk_fma_f32 v[48:49], v[84:85], v[52:53], v[48:49]
	v_mov_b32_dpp v55, v101 row_ror:1 row_mask:0xf bank_mask:0xf
	v_pk_fma_f32 v[48:49], v[80:81], v[50:51], v[48:49]
	v_mov_b32_dpp v59, v97 row_ror:15 row_mask:0xf bank_mask:0xf
	v_lshlrev_b32_e32 v52, 16, v101
	v_mul_f32_e32 v50, 0xbfb8aa3b, v48
	v_mul_f32_e32 v51, 0xbfb8aa3b, v49
	v_exp_f32_e32 v50, v50
	v_exp_f32_e32 v51, v51
	v_cndmask_b32_e64 v62, v55, v63, s[4:5]
	v_cndmask_b32_e64 v63, v111, v59, s[6:7]
	v_add_f32_e32 v50, 1.0, v50
	v_add_f32_e32 v51, 1.0, v51
	v_rcp_f32_e32 v50, v50
	v_rcp_f32_e32 v51, v51
	v_and_b32_e32 v53, 0xffff0000, v101
	v_mov_b32_dpp v56, v102 row_ror:1 row_mask:0xf bank_mask:0xf
	v_mov_b32_dpp v57, v103 row_ror:1 row_mask:0xf bank_mask:0xf
	v_pk_mul_f32 v[48:49], v[48:49], v[50:51]
	v_lshlrev_b32_e32 v50, 16, v63
	v_pk_mul_f32 v[44:45], v[44:45], v[48:49]
	v_lshlrev_b32_e32 v48, 16, v62
	v_and_b32_e32 v49, 0xffff0000, v62
	v_pk_fma_f32 v[48:49], v[94:95], v[48:49], v[90:91]
	v_and_b32_e32 v51, 0xffff0000, v63
	v_pk_fma_f32 v[48:49], v[86:87], v[52:53], v[48:49]
	v_cndmask_b32_e64 v104, v56, v108, s[4:5]
	v_pk_fma_f32 v[48:49], v[82:83], v[50:51], v[48:49]
	v_lshlrev_b32_e32 v52, 16, v102
	v_and_b32_e32 v53, 0xffff0000, v102
	v_mul_f32_e32 v50, 0xbfb8aa3b, v48
	v_mul_f32_e32 v51, 0xbfb8aa3b, v49
	v_exp_f32_e32 v50, v50
	v_exp_f32_e32 v51, v51
	v_cndmask_b32_e64 v106, v57, v109, s[4:5]
	v_add_f32_e32 v50, 1.0, v50
	v_add_f32_e32 v51, 1.0, v51
	v_rcp_f32_e32 v50, v50
	v_rcp_f32_e32 v51, v51
	s_nop 0
	v_pk_mul_f32 v[48:49], v[48:49], v[50:51]
	s_nop 0
	v_pk_mul_f32 v[46:47], v[46:47], v[48:49]
	v_lshlrev_b32_e32 v48, 16, v104
	v_and_b32_e32 v49, 0xffff0000, v104
	v_pk_fma_f32 v[48:49], v[76:77], v[48:49], v[72:73]
	v_lshlrev_b32_e32 v50, 16, v105
	v_and_b32_e32 v51, 0xffff0000, v105
	v_pk_fma_f32 v[48:49], v[68:69], v[52:53], v[48:49]
	v_lshlrev_b32_e32 v52, 16, v103
	v_pk_fma_f32 v[48:49], v[64:65], v[50:51], v[48:49]
	v_and_b32_e32 v53, 0xffff0000, v103
	s_nop 0
	v_mul_f32_e32 v50, 0xbfb8aa3b, v48
	v_mul_f32_e32 v51, 0xbfb8aa3b, v49
	v_exp_f32_e32 v50, v50
	v_exp_f32_e32 v51, v51
	v_add_f32_e32 v50, 1.0, v50
	v_add_f32_e32 v51, 1.0, v51
	v_rcp_f32_e32 v50, v50
	v_rcp_f32_e32 v51, v51
	s_nop 0
	v_pk_mul_f32 v[48:49], v[48:49], v[50:51]
	s_nop 0
	v_pk_mul_f32 v[48:49], v[40:41], v[48:49]
	v_lshlrev_b32_e32 v40, 16, v106
	v_and_b32_e32 v41, 0xffff0000, v106
	v_pk_fma_f32 v[40:41], v[78:79], v[40:41], v[74:75]
	v_lshlrev_b32_e32 v50, 16, v107
	v_and_b32_e32 v51, 0xffff0000, v107
	v_pk_fma_f32 v[40:41], v[70:71], v[52:53], v[40:41]
	s_nop 0
	v_pk_fma_f32 v[40:41], v[66:67], v[50:51], v[40:41]
	s_nop 0
	s_nop 0
	v_mul_f32_e32 v50, 0xbfb8aa3b, v40
	v_mul_f32_e32 v51, 0xbfb8aa3b, v41
	v_exp_f32_e32 v50, v50
	v_exp_f32_e32 v51, v51
	v_add_f32_e32 v50, 1.0, v50
	v_add_f32_e32 v51, 1.0, v51
	v_rcp_f32_e32 v50, v50
	v_rcp_f32_e32 v51, v51
	s_nop 0
	v_pk_mul_f32 v[40:41], v[40:41], v[50:51]
	s_nop 0
	v_pk_mul_f32 v[50:51], v[42:43], v[40:41]
	v_cvt_pk_bf16_f32 v40, v44, v45
	v_cvt_pk_bf16_f32 v41, v46, v47
	v_cvt_pk_bf16_f32 v42, v48, v49
	v_cvt_pk_bf16_f32 v43, v50, v51
	global_store_dwordx4 v[148:149], v[40:43], off offset:256
	ds_bpermute_b32 v40, v193, v96
	ds_bpermute_b32 v41, v193, v97
	v_mov_b32_dpp v42, v98 row_ror:1 row_mask:0xf bank_mask:0xf
	v_mov_b32_dpp v43, v99 row_ror:1 row_mask:0xf bank_mask:0xf
	v_cndmask_b32_e64 v45, v58, v117, s[6:7]
	s_waitcnt lgkmcnt(0)
	v_cndmask_b32_e64 v44, v40, v54, s[4:5]
	v_cndmask_b32_e64 v46, v41, v55, s[4:5]
	v_lshlrev_b32_e32 v40, 16, v44
	v_and_b32_e32 v41, 0xffff0000, v44
	v_cndmask_b32_e64 v48, v42, v56, s[4:5]
	v_cndmask_b32_e64 v50, v43, v57, s[4:5]
	v_lshlrev_b32_e32 v42, 16, v45
	v_and_b32_e32 v43, 0xffff0000, v45
	v_pk_fma_f32 v[40:41], v[92:93], v[40:41], v[88:89]
	v_lshlrev_b32_e32 v44, 16, v96
	v_and_b32_e32 v45, 0xffff0000, v96
	v_pk_fma_f32 v[40:41], v[84:85], v[44:45], v[40:41]
	v_cndmask_b32_e64 v47, v59, v116, s[6:7]
	v_pk_fma_f32 v[40:41], v[80:81], v[42:43], v[40:41]
	v_lshlrev_b32_e32 v44, 16, v97
	v_and_b32_e32 v45, 0xffff0000, v97
	v_mul_f32_e32 v42, 0xbfb8aa3b, v40
	v_mul_f32_e32 v43, 0xbfb8aa3b, v41
	v_exp_f32_e32 v42, v42
	v_exp_f32_e32 v43, v43
	v_cndmask_b32_e64 v49, v60, v115, s[6:7]
	v_cndmask_b32_e64 v51, v61, v114, s[6:7]
	v_add_f32_e32 v42, 1.0, v42
	v_add_f32_e32 v43, 1.0, v43
	v_rcp_f32_e32 v42, v42
	v_rcp_f32_e32 v43, v43
	s_nop 0
	v_pk_mul_f32 v[40:41], v[40:41], v[42:43]
	s_nop 0
	v_pk_mul_f32 v[36:37], v[36:37], v[40:41]
	v_lshlrev_b32_e32 v40, 16, v46
	v_and_b32_e32 v41, 0xffff0000, v46
	v_pk_fma_f32 v[40:41], v[94:95], v[40:41], v[90:91]
	v_lshlrev_b32_e32 v42, 16, v47
	v_and_b32_e32 v43, 0xffff0000, v47
	v_pk_fma_f32 v[40:41], v[86:87], v[44:45], v[40:41]
	v_lshlrev_b32_e32 v44, 16, v98
	v_pk_fma_f32 v[40:41], v[82:83], v[42:43], v[40:41]
	v_and_b32_e32 v45, 0xffff0000, v98
	s_nop 0
	v_mul_f32_e32 v42, 0xbfb8aa3b, v40
	v_mul_f32_e32 v43, 0xbfb8aa3b, v41
	v_exp_f32_e32 v42, v42
	v_exp_f32_e32 v43, v43
	v_add_f32_e32 v42, 1.0, v42
	v_add_f32_e32 v43, 1.0, v43
	v_rcp_f32_e32 v42, v42
	v_rcp_f32_e32 v43, v43
	s_nop 0
	v_pk_mul_f32 v[40:41], v[40:41], v[42:43]
	s_nop 0
	v_pk_mul_f32 v[38:39], v[38:39], v[40:41]
	v_lshlrev_b32_e32 v40, 16, v48
	v_and_b32_e32 v41, 0xffff0000, v48
	v_pk_fma_f32 v[40:41], v[76:77], v[40:41], v[72:73]
	v_lshlrev_b32_e32 v42, 16, v49
	v_and_b32_e32 v43, 0xffff0000, v49
	v_pk_fma_f32 v[40:41], v[68:69], v[44:45], v[40:41]
	v_lshlrev_b32_e32 v44, 16, v99
	v_pk_fma_f32 v[40:41], v[64:65], v[42:43], v[40:41]
	v_and_b32_e32 v45, 0xffff0000, v99
	s_nop 0
	v_mul_f32_e32 v42, 0xbfb8aa3b, v40
	v_mul_f32_e32 v43, 0xbfb8aa3b, v41
	v_exp_f32_e32 v42, v42
	v_exp_f32_e32 v43, v43
	v_add_f32_e32 v42, 1.0, v42
	v_add_f32_e32 v43, 1.0, v43
	v_rcp_f32_e32 v42, v42
	v_rcp_f32_e32 v43, v43
	s_nop 0
	v_pk_mul_f32 v[40:41], v[40:41], v[42:43]
	s_nop 0
	v_pk_mul_f32 v[40:41], v[32:33], v[40:41]
	v_lshlrev_b32_e32 v32, 16, v50
	v_and_b32_e32 v33, 0xffff0000, v50
	v_pk_fma_f32 v[32:33], v[78:79], v[32:33], v[74:75]
	v_lshlrev_b32_e32 v42, 16, v51
	v_and_b32_e32 v43, 0xffff0000, v51
	v_pk_fma_f32 v[32:33], v[70:71], v[44:45], v[32:33]
	s_nop 0
	v_pk_fma_f32 v[32:33], v[66:67], v[42:43], v[32:33]
	s_nop 0
	s_nop 0
	v_mul_f32_e32 v42, 0xbfb8aa3b, v32
	v_mul_f32_e32 v43, 0xbfb8aa3b, v33
	v_exp_f32_e32 v42, v42
	v_exp_f32_e32 v43, v43
	v_add_f32_e32 v42, 1.0, v42
	v_add_f32_e32 v43, 1.0, v43
	v_rcp_f32_e32 v42, v42
	v_rcp_f32_e32 v43, v43
	s_nop 0
	v_pk_mul_f32 v[32:33], v[32:33], v[42:43]
	s_nop 0
	v_pk_mul_f32 v[42:43], v[34:35], v[32:33]
	v_cvt_pk_bf16_f32 v32, v36, v37
	v_cvt_pk_bf16_f32 v33, v38, v39
	v_cvt_pk_bf16_f32 v34, v40, v41
	v_cvt_pk_bf16_f32 v35, v42, v43
	global_store_dwordx4 v[144:145], v[32:35], off offset:256
	global_load_dwordx4 v[48:51], v[150:151], off offset:256
	global_load_dwordx4 v[44:47], v[152:153], off offset:256
	global_load_dwordx4 v[40:43], v[154:155], off offset:256
	global_load_dwordx4 v[32:35], v[158:159], off offset:256
	global_load_dwordx4 v[52:55], v[162:163], off offset:256
	global_load_dwordx4 v[36:39], v[160:161], off offset:256
	s_waitcnt vmcnt(5)
	v_mov_b32_dpp v58, v48 row_ror:1 row_mask:0xf bank_mask:0xf
	v_mov_b32_dpp v56, v48 row_ror:15 row_mask:0xf bank_mask:0xf
	v_mov_b32_dpp v59, v49 row_ror:1 row_mask:0xf bank_mask:0xf
	s_waitcnt vmcnt(4)
	v_mov_b32_dpp v96, v44 row_ror:15 row_mask:0xf bank_mask:0xf
	v_mov_b32_dpp v57, v49 row_ror:15 row_mask:0xf bank_mask:0xf
	v_mov_b32_dpp v60, v50 row_ror:1 row_mask:0xf bank_mask:0xf
	v_mov_b32_dpp v62, v51 row_ror:1 row_mask:0xf bank_mask:0xf
	v_mov_b32_dpp v97, v45 row_ror:15 row_mask:0xf bank_mask:0xf
	s_waitcnt vmcnt(1)
	v_cndmask_b32_e64 v52, v52, 0, s[22:23]
	v_cndmask_b32_e64 v53, v53, 0, s[22:23]
	v_cndmask_b32_e64 v100, v58, v52, s[4:5]
	v_cndmask_b32_e64 v55, v55, 0, s[22:23]
	v_cndmask_b32_e64 v54, v54, 0, s[22:23]
	v_cndmask_b32_e64 v56, v56, v96, s[6:7]
	v_cndmask_b32_e64 v101, v59, v53, s[4:5]
	v_lshlrev_b32_e32 v52, 16, v100
	v_and_b32_e32 v53, 0xffff0000, v100
	v_cndmask_b32_e64 v102, v57, v97, s[6:7]
	v_cndmask_b32_e64 v103, v60, v54, s[4:5]
	v_cndmask_b32_e64 v104, v62, v55, s[4:5]
	v_lshlrev_b32_e32 v54, 16, v56
	v_and_b32_e32 v55, 0xffff0000, v56
	v_pk_fma_f32 v[52:53], v[92:93], v[52:53], v[88:89]
	v_lshlrev_b32_e32 v56, 16, v48
	v_and_b32_e32 v57, 0xffff0000, v48
	v_pk_fma_f32 v[52:53], v[84:85], v[56:57], v[52:53]
	v_mov_b32_dpp v61, v50 row_ror:15 row_mask:0xf bank_mask:0xf
	v_pk_fma_f32 v[52:53], v[80:81], v[54:55], v[52:53]
	v_mov_b32_dpp v98, v46 row_ror:15 row_mask:0xf bank_mask:0xf
	v_mov_b32_dpp v63, v51 row_ror:15 row_mask:0xf bank_mask:0xf
	v_mul_f32_e32 v48, 0xbfb8aa3b, v52
	v_exp_f32_e32 v48, v48
	v_cndmask_b32_e64 v61, v61, v98, s[6:7]
	v_mov_b32_dpp v99, v47 row_ror:15 row_mask:0xf bank_mask:0xf
	v_add_f32_e32 v48, 1.0, v48
	v_rcp_f32_e32 v54, v48
	v_mul_f32_e32 v48, 0xbfb8aa3b, v53
	v_exp_f32_e32 v48, v48
	v_cndmask_b32_e64 v63, v63, v99, s[6:7]
	v_add_f32_e32 v48, 1.0, v48
	v_rcp_f32_e32 v55, v48
	v_lshlrev_b32_e32 v48, 16, v49
	v_and_b32_e32 v49, 0xffff0000, v49
	v_pk_mul_f32 v[52:53], v[52:53], v[54:55]
	s_nop 0
	v_pk_mul_f32 v[28:29], v[28:29], v[52:53]
	v_lshlrev_b32_e32 v52, 16, v101
	v_and_b32_e32 v53, 0xffff0000, v101
	v_pk_mul_f32 v[52:53], v[94:95], v[52:53]
	v_lshlrev_b32_e32 v54, 16, v102
	v_and_b32_e32 v55, 0xffff0000, v102
	v_pk_fma_f32 v[48:49], v[86:87], v[48:49], v[52:53]
	s_nop 0
	v_pk_fma_f32 v[48:49], v[82:83], v[54:55], v[48:49]
	v_lshlrev_b32_e32 v54, 16, v50
	v_pk_add_f32 v[48:49], v[90:91], v[48:49]
	v_and_b32_e32 v55, 0xffff0000, v50
	v_mul_f32_e32 v52, 0xbfb8aa3b, v48
	v_mul_f32_e32 v53, 0xbfb8aa3b, v49
	v_exp_f32_e32 v52, v52
	v_exp_f32_e32 v53, v53
	v_add_f32_e32 v52, 1.0, v52
	v_add_f32_e32 v53, 1.0, v53
	v_rcp_f32_e32 v52, v52
	v_rcp_f32_e32 v53, v53
	s_nop 0
	v_pk_mul_f32 v[48:49], v[48:49], v[52:53]
	s_nop 0
	v_pk_mul_f32 v[30:31], v[30:31], v[48:49]
	v_lshlrev_b32_e32 v48, 16, v103
	v_and_b32_e32 v49, 0xffff0000, v103
	v_pk_fma_f32 v[48:49], v[76:77], v[48:49], v[72:73]
	v_lshlrev_b32_e32 v52, 16, v61
	v_and_b32_e32 v53, 0xffff0000, v61
	v_pk_fma_f32 v[48:49], v[68:69], v[54:55], v[48:49]
	s_nop 0
	v_pk_fma_f32 v[48:49], v[64:65], v[52:53], v[48:49]
	s_nop 0
	s_nop 0
	v_mul_f32_e32 v50, 0xbfb8aa3b, v48
	v_exp_f32_e32 v50, v50
	s_nop 0
	v_add_f32_e32 v50, 1.0, v50
	v_rcp_f32_e32 v52, v50
	v_mul_f32_e32 v50, 0xbfb8aa3b, v49
	v_exp_f32_e32 v50, v50
	s_nop 0
	v_add_f32_e32 v50, 1.0, v50
	v_rcp_f32_e32 v53, v50
	v_lshlrev_b32_e32 v50, 16, v51
	v_and_b32_e32 v51, 0xffff0000, v51
	v_pk_mul_f32 v[48:49], v[48:49], v[52:53]
	s_nop 0
	v_pk_mul_f32 v[48:49], v[24:25], v[48:49]
	v_lshlrev_b32_e32 v24, 16, v104
	v_and_b32_e32 v25, 0xffff0000, v104
	v_pk_fma_f32 v[24:25], v[78:79], v[24:25], v[74:75]
	v_lshlrev_b32_e32 v52, 16, v63
	v_and_b32_e32 v53, 0xffff0000, v63
	v_pk_fma_f32 v[24:25], v[70:71], v[50:51], v[24:25]
	s_nop 0
	v_pk_fma_f32 v[24:25], v[66:67], v[52:53], v[24:25]
	v_mov_b32_dpp v52, v42 row_ror:15 row_mask:0xf bank_mask:0xf
	v_mov_b32_dpp v53, v43 row_ror:15 row_mask:0xf bank_mask:0xf
	v_mul_f32_e32 v50, 0xbfb8aa3b, v24
	v_mul_f32_e32 v51, 0xbfb8aa3b, v25
	v_exp_f32_e32 v50, v50
	v_exp_f32_e32 v51, v51
	v_cndmask_b32_e64 v57, v98, v52, s[6:7]
	v_add_f32_e32 v50, 1.0, v50
	v_add_f32_e32 v51, 1.0, v51
	v_rcp_f32_e32 v50, v50
	v_rcp_f32_e32 v51, v51
	s_nop 0
	v_pk_mul_f32 v[24:25], v[24:25], v[50:51]
	s_nop 0
	v_pk_mul_f32 v[50:51], v[26:27], v[24:25]
	v_cvt_pk_bf16_f32 v25, v30, v31
	v_mov_b32_dpp v30, v44 row_ror:1 row_mask:0xf bank_mask:0xf
	v_cvt_pk_bf16_f32 v27, v50, v51
	v_mov_b32_dpp v50, v40 row_ror:15 row_mask:0xf bank_mask:0xf
	v_cvt_pk_bf16_f32 v24, v28, v29
	v_cvt_pk_bf16_f32 v26, v48, v49
	global_store_dwordx4 v[124:125], v[24:27], off offset:256
	v_lshlrev_b32_e32 v28, 16, v44
	v_and_b32_e32 v29, 0xffff0000, v44
	v_cndmask_b32_e64 v25, v30, v58, s[4:5]
	v_lshlrev_b32_e32 v24, 16, v25
	v_and_b32_e32 v25, 0xffff0000, v25
	v_cndmask_b32_e64 v27, v96, v50, s[6:7]
	v_pk_fma_f32 v[24:25], v[92:93], v[24:25], v[88:89]
	v_lshlrev_b32_e32 v26, 16, v27
	v_and_b32_e32 v27, 0xffff0000, v27
	v_pk_fma_f32 v[24:25], v[84:85], v[28:29], v[24:25]
	v_mov_b32_dpp v31, v45 row_ror:1 row_mask:0xf bank_mask:0xf
	v_pk_fma_f32 v[24:25], v[80:81], v[26:27], v[24:25]
	v_mov_b32_dpp v51, v41 row_ror:15 row_mask:0xf bank_mask:0xf
	v_lshlrev_b32_e32 v28, 16, v45
	v_mul_f32_e32 v26, 0xbfb8aa3b, v24
	v_mul_f32_e32 v27, 0xbfb8aa3b, v25
	v_exp_f32_e32 v26, v26
	v_exp_f32_e32 v27, v27
	v_cndmask_b32_e64 v54, v31, v59, s[4:5]
	v_cndmask_b32_e64 v55, v97, v51, s[6:7]
	v_add_f32_e32 v26, 1.0, v26
	v_add_f32_e32 v27, 1.0, v27
	v_rcp_f32_e32 v26, v26
	v_rcp_f32_e32 v27, v27
	v_and_b32_e32 v29, 0xffff0000, v45
	v_mov_b32_dpp v48, v46 row_ror:1 row_mask:0xf bank_mask:0xf
	v_mov_b32_dpp v49, v47 row_ror:1 row_mask:0xf bank_mask:0xf
	v_pk_mul_f32 v[24:25], v[24:25], v[26:27]
	v_lshlrev_b32_e32 v26, 16, v55
	v_pk_mul_f32 v[20:21], v[20:21], v[24:25]
	v_lshlrev_b32_e32 v24, 16, v54
	v_and_b32_e32 v25, 0xffff0000, v54
	v_pk_fma_f32 v[24:25], v[94:95], v[24:25], v[90:91]
	v_and_b32_e32 v27, 0xffff0000, v55
	v_pk_fma_f32 v[24:25], v[86:87], v[28:29], v[24:25]
	v_cndmask_b32_e64 v56, v48, v60, s[4:5]
	v_pk_fma_f32 v[24:25], v[82:83], v[26:27], v[24:25]
	v_lshlrev_b32_e32 v28, 16, v46
	v_and_b32_e32 v29, 0xffff0000, v46
	v_mul_f32_e32 v26, 0xbfb8aa3b, v24
	v_mul_f32_e32 v27, 0xbfb8aa3b, v25
	v_exp_f32_e32 v26, v26
	v_exp_f32_e32 v27, v27
	v_cndmask_b32_e64 v58, v49, v62, s[4:5]
	v_cndmask_b32_e64 v59, v99, v53, s[6:7]
	v_add_f32_e32 v26, 1.0, v26
	v_add_f32_e32 v27, 1.0, v27
	v_rcp_f32_e32 v26, v26
	v_rcp_f32_e32 v27, v27
	s_nop 0
	v_pk_mul_f32 v[24:25], v[24:25], v[26:27]
	s_nop 0
	v_pk_mul_f32 v[22:23], v[22:23], v[24:25]
	v_lshlrev_b32_e32 v24, 16, v56
	v_and_b32_e32 v25, 0xffff0000, v56
	v_pk_fma_f32 v[24:25], v[76:77], v[24:25], v[72:73]
	v_lshlrev_b32_e32 v26, 16, v57
	v_and_b32_e32 v27, 0xffff0000, v57
	v_pk_fma_f32 v[24:25], v[68:69], v[28:29], v[24:25]
	v_lshlrev_b32_e32 v28, 16, v47
	v_pk_fma_f32 v[24:25], v[64:65], v[26:27], v[24:25]
	v_and_b32_e32 v29, 0xffff0000, v47
	s_nop 0
	v_mul_f32_e32 v26, 0xbfb8aa3b, v24
	v_mul_f32_e32 v27, 0xbfb8aa3b, v25
	v_exp_f32_e32 v26, v26
	v_exp_f32_e32 v27, v27
	v_add_f32_e32 v26, 1.0, v26
	v_add_f32_e32 v27, 1.0, v27
	v_rcp_f32_e32 v26, v26
	v_rcp_f32_e32 v27, v27
	s_nop 0
	v_pk_mul_f32 v[24:25], v[24:25], v[26:27]
	s_nop 0
	v_pk_mul_f32 v[24:25], v[16:17], v[24:25]
	v_lshlrev_b32_e32 v16, 16, v58
	v_and_b32_e32 v17, 0xffff0000, v58
	v_pk_fma_f32 v[16:17], v[78:79], v[16:17], v[74:75]
	v_lshlrev_b32_e32 v26, 16, v59
	v_and_b32_e32 v27, 0xffff0000, v59
	v_pk_fma_f32 v[16:17], v[70:71], v[28:29], v[16:17]
	v_mov_b32_dpp v28, v34 row_ror:15 row_mask:0xf bank_mask:0xf
	v_pk_fma_f32 v[16:17], v[66:67], v[26:27], v[16:17]
	v_mov_b32_dpp v29, v35 row_ror:15 row_mask:0xf bank_mask:0xf
	v_cndmask_b32_e64 v45, v52, v28, s[6:7]
	v_mul_f32_e32 v26, 0xbfb8aa3b, v16
	v_mul_f32_e32 v27, 0xbfb8aa3b, v17
	v_exp_f32_e32 v26, v26
	v_exp_f32_e32 v27, v27
	v_cndmask_b32_e64 v47, v53, v29, s[6:7]
	v_add_f32_e32 v26, 1.0, v26
	v_add_f32_e32 v27, 1.0, v27
	v_rcp_f32_e32 v26, v26
	v_rcp_f32_e32 v27, v27
	s_nop 0
	v_pk_mul_f32 v[16:17], v[16:17], v[26:27]
	s_nop 0
	v_pk_mul_f32 v[26:27], v[18:19], v[16:17]
	v_cvt_pk_bf16_f32 v17, v22, v23
	v_mov_b32_dpp v22, v40 row_ror:1 row_mask:0xf bank_mask:0xf
	v_cvt_pk_bf16_f32 v19, v26, v27
	v_mov_b32_dpp v26, v32 row_ror:15 row_mask:0xf bank_mask:0xf
	v_cvt_pk_bf16_f32 v16, v20, v21
	v_cvt_pk_bf16_f32 v18, v24, v25
	global_store_dwordx4 v[126:127], v[16:19], off offset:256
	v_lshlrev_b32_e32 v20, 16, v40
	v_and_b32_e32 v21, 0xffff0000, v40
	v_cndmask_b32_e64 v17, v22, v30, s[4:5]
	v_lshlrev_b32_e32 v16, 16, v17
	v_and_b32_e32 v17, 0xffff0000, v17
	v_cndmask_b32_e64 v19, v50, v26, s[6:7]
	v_pk_fma_f32 v[16:17], v[92:93], v[16:17], v[88:89]
	v_lshlrev_b32_e32 v18, 16, v19
	v_and_b32_e32 v19, 0xffff0000, v19
	v_pk_fma_f32 v[16:17], v[84:85], v[20:21], v[16:17]
	v_mov_b32_dpp v23, v41 row_ror:1 row_mask:0xf bank_mask:0xf
	v_pk_fma_f32 v[16:17], v[80:81], v[18:19], v[16:17]
	v_mov_b32_dpp v27, v33 row_ror:15 row_mask:0xf bank_mask:0xf
	v_lshlrev_b32_e32 v20, 16, v41
	v_mul_f32_e32 v18, 0xbfb8aa3b, v16
	v_mul_f32_e32 v19, 0xbfb8aa3b, v17
	v_exp_f32_e32 v18, v18
	v_exp_f32_e32 v19, v19
	v_cndmask_b32_e64 v30, v23, v31, s[4:5]
	v_cndmask_b32_e64 v31, v51, v27, s[6:7]
	v_add_f32_e32 v18, 1.0, v18
	v_add_f32_e32 v19, 1.0, v19
	v_rcp_f32_e32 v18, v18
	v_rcp_f32_e32 v19, v19
	v_and_b32_e32 v21, 0xffff0000, v41
	v_mov_b32_dpp v24, v42 row_ror:1 row_mask:0xf bank_mask:0xf
	v_mov_b32_dpp v25, v43 row_ror:1 row_mask:0xf bank_mask:0xf
	v_pk_mul_f32 v[16:17], v[16:17], v[18:19]
	v_lshlrev_b32_e32 v18, 16, v31
	v_pk_mul_f32 v[12:13], v[12:13], v[16:17]
	v_lshlrev_b32_e32 v16, 16, v30
	v_and_b32_e32 v17, 0xffff0000, v30
	v_pk_fma_f32 v[16:17], v[94:95], v[16:17], v[90:91]
	v_and_b32_e32 v19, 0xffff0000, v31
	v_pk_fma_f32 v[16:17], v[86:87], v[20:21], v[16:17]
	v_cndmask_b32_e64 v44, v24, v48, s[4:5]
	v_pk_fma_f32 v[16:17], v[82:83], v[18:19], v[16:17]
	v_lshlrev_b32_e32 v20, 16, v42
	v_and_b32_e32 v21, 0xffff0000, v42
	v_mul_f32_e32 v18, 0xbfb8aa3b, v16
	v_mul_f32_e32 v19, 0xbfb8aa3b, v17
	v_exp_f32_e32 v18, v18
	v_exp_f32_e32 v19, v19
	v_cndmask_b32_e64 v46, v25, v49, s[4:5]
	v_add_f32_e32 v18, 1.0, v18
	v_add_f32_e32 v19, 1.0, v19
	v_rcp_f32_e32 v18, v18
	v_rcp_f32_e32 v19, v19
	s_nop 0
	v_pk_mul_f32 v[16:17], v[16:17], v[18:19]
	s_nop 0
	v_pk_mul_f32 v[14:15], v[14:15], v[16:17]
	v_lshlrev_b32_e32 v16, 16, v44
	v_and_b32_e32 v17, 0xffff0000, v44
	v_pk_fma_f32 v[16:17], v[76:77], v[16:17], v[72:73]
	v_lshlrev_b32_e32 v18, 16, v45
	v_and_b32_e32 v19, 0xffff0000, v45
	v_pk_fma_f32 v[16:17], v[68:69], v[20:21], v[16:17]
	v_lshlrev_b32_e32 v20, 16, v43
	v_pk_fma_f32 v[16:17], v[64:65], v[18:19], v[16:17]
	v_and_b32_e32 v21, 0xffff0000, v43
	s_nop 0
	v_mul_f32_e32 v18, 0xbfb8aa3b, v16
	v_mul_f32_e32 v19, 0xbfb8aa3b, v17
	v_exp_f32_e32 v18, v18
	v_exp_f32_e32 v19, v19
	v_add_f32_e32 v18, 1.0, v18
	v_add_f32_e32 v19, 1.0, v19
	v_rcp_f32_e32 v18, v18
	v_rcp_f32_e32 v19, v19
	s_nop 0
	v_pk_mul_f32 v[16:17], v[16:17], v[18:19]
	s_nop 0
	v_pk_mul_f32 v[16:17], v[8:9], v[16:17]
	v_lshlrev_b32_e32 v8, 16, v46
	v_and_b32_e32 v9, 0xffff0000, v46
	v_pk_fma_f32 v[8:9], v[78:79], v[8:9], v[74:75]
	v_lshlrev_b32_e32 v18, 16, v47
	v_and_b32_e32 v19, 0xffff0000, v47
	v_pk_fma_f32 v[8:9], v[70:71], v[20:21], v[8:9]
	s_nop 0
	v_pk_fma_f32 v[8:9], v[66:67], v[18:19], v[8:9]
	s_nop 0
	s_nop 0
	v_mul_f32_e32 v18, 0xbfb8aa3b, v8
	v_mul_f32_e32 v19, 0xbfb8aa3b, v9
	v_exp_f32_e32 v18, v18
	v_exp_f32_e32 v19, v19
	v_add_f32_e32 v18, 1.0, v18
	v_add_f32_e32 v19, 1.0, v19
	v_rcp_f32_e32 v18, v18
	v_rcp_f32_e32 v19, v19
	s_nop 0
	v_pk_mul_f32 v[8:9], v[8:9], v[18:19]
	s_nop 0
	v_pk_mul_f32 v[18:19], v[10:11], v[8:9]
	v_cvt_pk_bf16_f32 v8, v12, v13
	v_cvt_pk_bf16_f32 v9, v14, v15
	v_cvt_pk_bf16_f32 v10, v16, v17
	v_cvt_pk_bf16_f32 v11, v18, v19
	global_store_dwordx4 v[132:133], v[8:11], off offset:256
	ds_bpermute_b32 v8, v193, v32
	ds_bpermute_b32 v9, v193, v33
	v_mov_b32_dpp v10, v34 row_ror:1 row_mask:0xf bank_mask:0xf
	v_mov_b32_dpp v11, v35 row_ror:1 row_mask:0xf bank_mask:0xf
	s_waitcnt vmcnt(3)
	v_cndmask_b32_e64 v12, v39, 0, vcc
	s_waitcnt lgkmcnt(0)
	v_cndmask_b32_e64 v16, v8, v22, s[4:5]
	v_cndmask_b32_e64 v13, v38, 0, vcc
	v_cndmask_b32_e64 v15, v36, 0, vcc
	v_cndmask_b32_e64 v17, v9, v23, s[4:5]
	v_lshlrev_b32_e32 v8, 16, v16
	v_and_b32_e32 v9, 0xffff0000, v16
	v_cndmask_b32_e64 v15, v26, v15, s[6:7]
	v_cndmask_b32_e64 v19, v28, v13, s[6:7]
	v_cndmask_b32_e64 v21, v29, v12, s[6:7]
	v_pk_fma_f32 v[8:9], v[92:93], v[8:9], v[88:89]
	v_lshlrev_b32_e32 v12, 16, v32
	v_and_b32_e32 v13, 0xffff0000, v32
	v_cndmask_b32_e64 v18, v10, v24, s[4:5]
	v_cndmask_b32_e64 v20, v11, v25, s[4:5]
	v_lshlrev_b32_e32 v10, 16, v15
	v_and_b32_e32 v11, 0xffff0000, v15
	v_pk_fma_f32 v[8:9], v[84:85], v[12:13], v[8:9]
	v_cndmask_b32_e64 v14, v37, 0, vcc
	v_pk_fma_f32 v[8:9], v[80:81], v[10:11], v[8:9]
	v_cndmask_b32_e64 v14, v27, v14, s[6:7]
	v_lshlrev_b32_e32 v12, 16, v33
	v_mul_f32_e32 v10, 0xbfb8aa3b, v8
	v_mul_f32_e32 v11, 0xbfb8aa3b, v9
	v_exp_f32_e32 v10, v10
	v_exp_f32_e32 v11, v11
	v_and_b32_e32 v13, 0xffff0000, v33
	s_andn2_b64 vcc, exec, s[68:69]
	v_add_f32_e32 v10, 1.0, v10
	v_add_f32_e32 v11, 1.0, v11
	v_rcp_f32_e32 v10, v10
	v_rcp_f32_e32 v11, v11
	s_nop 0
	v_pk_mul_f32 v[8:9], v[8:9], v[10:11]
	s_nop 0
	v_pk_mul_f32 v[4:5], v[4:5], v[8:9]
	v_lshlrev_b32_e32 v8, 16, v17
	v_and_b32_e32 v9, 0xffff0000, v17
	v_pk_fma_f32 v[8:9], v[94:95], v[8:9], v[90:91]
	v_lshlrev_b32_e32 v10, 16, v14
	v_and_b32_e32 v11, 0xffff0000, v14
	v_pk_fma_f32 v[8:9], v[86:87], v[12:13], v[8:9]
	v_lshlrev_b32_e32 v12, 16, v34
	v_pk_fma_f32 v[8:9], v[82:83], v[10:11], v[8:9]
	v_and_b32_e32 v13, 0xffff0000, v34
	s_nop 0
	v_mul_f32_e32 v10, 0xbfb8aa3b, v8
	v_mul_f32_e32 v11, 0xbfb8aa3b, v9
	v_exp_f32_e32 v10, v10
	v_exp_f32_e32 v11, v11
	v_add_f32_e32 v10, 1.0, v10
	v_add_f32_e32 v11, 1.0, v11
	v_rcp_f32_e32 v10, v10
	v_rcp_f32_e32 v11, v11
	s_nop 0
	v_pk_mul_f32 v[8:9], v[8:9], v[10:11]
	s_nop 0
	v_pk_mul_f32 v[6:7], v[6:7], v[8:9]
	v_lshlrev_b32_e32 v8, 16, v18
	v_and_b32_e32 v9, 0xffff0000, v18
	v_pk_fma_f32 v[8:9], v[76:77], v[8:9], v[72:73]
	v_lshlrev_b32_e32 v10, 16, v19
	v_and_b32_e32 v11, 0xffff0000, v19
	v_pk_fma_f32 v[8:9], v[68:69], v[12:13], v[8:9]
	v_lshlrev_b32_e32 v12, 16, v35
	v_pk_fma_f32 v[8:9], v[64:65], v[10:11], v[8:9]
	v_and_b32_e32 v13, 0xffff0000, v35
	s_nop 0
	v_mul_f32_e32 v10, 0xbfb8aa3b, v8
	v_mul_f32_e32 v11, 0xbfb8aa3b, v9
	v_exp_f32_e32 v10, v10
	v_exp_f32_e32 v11, v11
	v_add_f32_e32 v10, 1.0, v10
	v_add_f32_e32 v11, 1.0, v11
	v_rcp_f32_e32 v10, v10
	v_rcp_f32_e32 v11, v11
	s_nop 0
	v_pk_mul_f32 v[8:9], v[8:9], v[10:11]
	s_nop 0
	v_pk_mul_f32 v[8:9], v[0:1], v[8:9]
	v_lshlrev_b32_e32 v0, 16, v20
	v_and_b32_e32 v1, 0xffff0000, v20
	v_pk_fma_f32 v[0:1], v[78:79], v[0:1], v[74:75]
	v_lshlrev_b32_e32 v10, 16, v21
	v_and_b32_e32 v11, 0xffff0000, v21
	v_pk_fma_f32 v[0:1], v[70:71], v[12:13], v[0:1]
	s_nop 0
	v_pk_fma_f32 v[0:1], v[66:67], v[10:11], v[0:1]
	s_nop 0
	s_nop 0
	v_mul_f32_e32 v10, 0xbfb8aa3b, v0
	v_mul_f32_e32 v11, 0xbfb8aa3b, v1
	v_exp_f32_e32 v10, v10
	v_exp_f32_e32 v11, v11
	v_add_f32_e32 v10, 1.0, v10
	v_add_f32_e32 v11, 1.0, v11
	v_rcp_f32_e32 v10, v10
	v_rcp_f32_e32 v11, v11
	s_nop 0
	v_pk_mul_f32 v[0:1], v[0:1], v[10:11]
	s_nop 0
	v_pk_mul_f32 v[10:11], v[2:3], v[0:1]
	v_cvt_pk_bf16_f32 v0, v4, v5
	v_cvt_pk_bf16_f32 v1, v6, v7
	v_cvt_pk_bf16_f32 v2, v8, v9
	v_cvt_pk_bf16_f32 v3, v10, v11
	global_store_dwordx4 v[112:113], v[0:3], off offset:256
	s_cbranch_vccnz .LBB0_1053
	s_andn2_b64 vcc, exec, s[36:37]
	s_cbranch_vccnz .LBB0_1052
	s_barrier
	s_branch .LBB0_1052
